# fused prompt memory attention: all 16 K fragment pieces loaded at once; first 8 V pieces loaded early in the S phase into dead registers, the rest right behind the barrier (were 2+2 dependent load/sto
# speedup vs baseline: 1.0108x; 1.0068x over previous
; __device__ __forceinline__ int fresh_lane() { int l; asm volatile("v_mbcnt_lo_u32_b32 %0, -1, 0\n\tv_mbcnt_hi_u32_b32 %0, -1, %0" : "=v"(l)); return l; }
; #define LAS __attribute__((address_space(3)))
; #define LAS __attribute__((address_space(3)))
; __device__ __forceinline__ void memattn_tile_lds(const Ctx& C, int pm, int h, unsigned char* lds) {
;     const int lane = fresh_lane(), tid = C.wave * 64 + lane, r32 = lane & 31, hi = lane >> 5; const int b = pm >> 5; const int row = 256 * pm + 32 * C.wave + r32;
;     LAS unsigned char* ldsl = (LAS unsigned char*)lds;
;     const u32x4* kG = (const u32x4*)(C.ws + WS_MKF) + (size_t)((b * 4 + h) * 8 * 16) * 64;
;     const u32x4* vG = (const u32x4*)(C.ws + WS_MVF) + (size_t)((b * 4 + h) * 8 * 16) * 64;
; #pragma unroll 1
;     for (int i0 = 0; i0 < 16; i0 += 8) { u32x4 t[8];
; #pragma unroll
;       for (int i = 0; i < 8; ++i) t[i] = kG[(i0 + i) * 512 + tid];
; #pragma unroll
;       for (int i = 0; i < 8; ++i) *(LAS u32x4*)(ldsl + (size_t)((i0 + i) * 512 + tid) * 16) = t[i]; }
;     __builtin_amdgcn_sched_barrier(0);
;     const bf16_t* qp = (const bf16_t*)(C.ws + WS_QMEM) + (size_t)row * 1024 + h * 256 + hi * 8;
;     bf16x8 qf[16];
; #pragma unroll
;     for (int ks = 0; ks < 16; ++ks) qf[ks] = *(const bf16x8*)(qp + ks * 16);
;     const float c = (1.0f / sqrtf(((const float*)(C.ws + ACC_SSQ))[row * 4 + h] * (1.f / 256.f) + EPS)) * (0.0625f * 1.4426950408889634f);
;     __syncthreads();
;     const LAS unsigned char* fL0 = ldsl + lane * 16; const LAS unsigned char* fL1 = fL0 + 65536;
.LBB0_3018:
	v_lshlrev_b32_e32 v2, 4, v139
	v_mov_b32_e32 v3, 0
	s_waitcnt vmcnt(0)
	v_lshl_add_u64 v[36:37], s[0:1], 0, v[2:3]
	s_mov_b32 s20, 0x2000
	s_mov_b32 s21, 0
	global_load_dwordx4 v[4:7], v[36:37], off
	v_lshl_add_u64 v[36:37], v[36:37], 0, s[20:21]
	global_load_dwordx4 v[8:11], v[36:37], off
	v_lshl_add_u64 v[36:37], v[36:37], 0, s[20:21]
	global_load_dwordx4 v[12:15], v[36:37], off
	v_lshl_add_u64 v[36:37], v[36:37], 0, s[20:21]
	global_load_dwordx4 v[16:19], v[36:37], off
	v_lshl_add_u64 v[36:37], v[36:37], 0, s[20:21]
	global_load_dwordx4 v[20:23], v[36:37], off
	v_lshl_add_u64 v[36:37], v[36:37], 0, s[20:21]
	global_load_dwordx4 v[24:27], v[36:37], off
	v_lshl_add_u64 v[36:37], v[36:37], 0, s[20:21]
	global_load_dwordx4 v[28:31], v[36:37], off
	v_lshl_add_u64 v[36:37], v[36:37], 0, s[20:21]
	global_load_dwordx4 v[32:35], v[36:37], off
	v_lshl_add_u64 v[36:37], v[36:37], 0, s[20:21]
	global_load_dwordx4 v[204:207], v[36:37], off
	v_lshl_add_u64 v[36:37], v[36:37], 0, s[20:21]
	global_load_dwordx4 v[208:211], v[36:37], off
	v_lshl_add_u64 v[36:37], v[36:37], 0, s[20:21]
	global_load_dwordx4 v[212:215], v[36:37], off
	v_lshl_add_u64 v[36:37], v[36:37], 0, s[20:21]
	global_load_dwordx4 v[216:219], v[36:37], off
	v_lshl_add_u64 v[36:37], v[36:37], 0, s[20:21]
	global_load_dwordx4 v[220:223], v[36:37], off
	v_lshl_add_u64 v[36:37], v[36:37], 0, s[20:21]
	global_load_dwordx4 v[224:227], v[36:37], off
	v_lshl_add_u64 v[36:37], v[36:37], 0, s[20:21]
	global_load_dwordx4 v[228:231], v[36:37], off
	v_lshl_add_u64 v[36:37], v[36:37], 0, s[20:21]
	global_load_dwordx4 v[232:235], v[36:37], off
	v_add_u32_e32 v38, 0x10000, v141
	s_waitcnt vmcnt(15)
	ds_write_b128 v141, v[4:7]
	s_waitcnt vmcnt(14)
	ds_write_b128 v141, v[8:11] offset:8192
	s_waitcnt vmcnt(13)
	ds_write_b128 v141, v[12:15] offset:16384
	s_waitcnt vmcnt(12)
	ds_write_b128 v141, v[16:19] offset:24576
	s_waitcnt vmcnt(11)
	ds_write_b128 v141, v[20:23] offset:32768
	s_waitcnt vmcnt(10)
	ds_write_b128 v141, v[24:27] offset:40960
	s_waitcnt vmcnt(9)
	ds_write_b128 v141, v[28:31] offset:49152
	s_waitcnt vmcnt(8)
	ds_write_b128 v141, v[32:35] offset:57344
	s_waitcnt vmcnt(7)
	ds_write_b128 v38, v[204:207]
	s_waitcnt vmcnt(6)
	ds_write_b128 v38, v[208:211] offset:8192
	s_waitcnt vmcnt(5)
	ds_write_b128 v38, v[212:215] offset:16384
	s_waitcnt vmcnt(4)
	ds_write_b128 v38, v[216:219] offset:24576
	s_waitcnt vmcnt(3)
	ds_write_b128 v38, v[220:223] offset:32768
	s_waitcnt vmcnt(2)
	ds_write_b128 v38, v[224:227] offset:40960
	s_waitcnt vmcnt(1)
	ds_write_b128 v38, v[228:231] offset:49152
	s_waitcnt vmcnt(0)
	ds_write_b128 v38, v[232:235] offset:57344
	s_mov_b64 s[14:15], 0
	s_mov_b32 s20, 8
	s_lshl_b32 s0, s19, 8
	s_add_i32 s0, s0, s43
	v_ashrrev_i32_e32 v140, 5, v0
	v_and_or_b32 v136, v0, 31, s0
	v_ashrrev_i32_e32 v137, 31, v136
	v_lshlrev_b64 v[2:3], 11, v[136:137]
	s_lshl_b32 s14, s18, 8
	v_lshl_add_u64 v[2:3], s[12:13], 0, v[2:3]
	s_ashr_i32 s15, s14, 31
	v_lshlrev_b32_e32 v4, 3, v140
	v_lshl_add_u64 v[2:3], s[14:15], 1, v[2:3]
	v_ashrrev_i32_e32 v5, 31, v4
	v_lshl_add_u64 v[2:3], v[4:5], 1, v[2:3]
	global_load_dwordx4 v[96:99], v[2:3], off
	global_load_dwordx4 v[92:95], v[2:3], off offset:32
	global_load_dwordx4 v[88:91], v[2:3], off offset:64
	global_load_dwordx4 v[80:83], v[2:3], off offset:96
	global_load_dwordx4 v[76:79], v[2:3], off offset:128
	global_load_dwordx4 v[72:75], v[2:3], off offset:160
	global_load_dwordx4 v[84:87], v[2:3], off offset:192
	v_lshl_add_u32 v4, v136, 2, s18
	v_ashrrev_i32_e32 v5, 31, v4
	v_lshl_add_u32 v138, v0, 4, 0
	v_lshl_add_u64 v[0:1], v[4:5], 2, s[8:9]
	global_load_dword v24, v[0:1], off
	global_load_dwordx4 v[132:135], v[2:3], off offset:224
	global_load_dwordx4 v[120:123], v[2:3], off offset:256
	global_load_dwordx4 v[116:119], v[2:3], off offset:288
	global_load_dwordx4 v[112:115], v[2:3], off offset:320
	global_load_dwordx4 v[108:111], v[2:3], off offset:352
	global_load_dwordx4 v[104:107], v[2:3], off offset:384
	global_load_dwordx4 v[100:103], v[2:3], off offset:416
	global_load_dwordx4 v[68:71], v[2:3], off offset:448
	global_load_dwordx4 v[64:67], v[2:3], off offset:480
	s_waitcnt lgkmcnt(0)
	s_barrier
	ds_read_b128 v[0:3], v138
	ds_read_b128 v[16:19], v138 offset:1024
	v_mov_b32_e32 v25, 0x358637bd
	s_mov_b32 s0, 0xf800000
	v_mov_b32_e32 v28, 0x260
	v_add_u32_e32 v142, 0x10000, v138
	v_add_u32_e32 v143, 0x10400, v138
	v_add_u32_e32 v144, 0x10800, v138
	v_add_u32_e32 v146, 0x10c00, v138
	v_add_u32_e32 v145, 0x11000, v138
	v_add_u32_e32 v148, 0x11400, v138
	v_add_u32_e32 v147, 0x11800, v138
	v_add_u32_e32 v149, 0x11c00, v138
	v_add_u32_e32 v150, 0x12000, v138
	v_add_u32_e32 v151, 0x12400, v138
	v_add_u32_e32 v152, 0x12800, v138
	v_add_u32_e32 v154, 0x12c00, v138
	v_add_u32_e32 v153, 0x13000, v138
	v_add_u32_e32 v156, 0x13400, v138
	v_add_u32_e32 v155, 0x13800, v138
	v_add_u32_e32 v157, 0x13c00, v138
	v_add_u32_e32 v158, 0x14000, v138
	v_add_u32_e32 v159, 0x14400, v138
	v_add_u32_e32 v160, 0x14800, v138
	v_add_u32_e32 v162, 0x14c00, v138
	v_add_u32_e32 v161, 0x15000, v138
	v_add_u32_e32 v164, 0x15400, v138
	v_add_u32_e32 v163, 0x15800, v138
	v_add_u32_e32 v165, 0x15c00, v138
	v_add_u32_e32 v166, 0x16000, v138
	v_add_u32_e32 v167, 0x16400, v138
	v_add_u32_e32 v168, 0x16800, v138
	v_add_u32_e32 v170, 0x16c00, v138
	v_add_u32_e32 v169, 0x17000, v138
	v_add_u32_e32 v172, 0x17400, v138
	v_add_u32_e32 v171, 0x17800, v138
	v_add_u32_e32 v173, 0x17c00, v138
	v_add_u32_e32 v174, 0x18000, v138
	v_add_u32_e32 v175, 0x18400, v138
	v_add_u32_e32 v176, 0x18800, v138
	v_add_u32_e32 v178, 0x18c00, v138
	v_add_u32_e32 v177, 0x19000, v138
	v_add_u32_e32 v180, 0x19400, v138
	v_add_u32_e32 v179, 0x19800, v138
	v_add_u32_e32 v181, 0x19c00, v138
	v_add_u32_e32 v182, 0x1a000, v138
	v_add_u32_e32 v184, 0x1a400, v138
	v_add_u32_e32 v185, 0x1a800, v138
	v_add_u32_e32 v187, 0x1ac00, v138
	v_add_u32_e32 v186, 0x1b000, v138
	v_add_u32_e32 v189, 0x1b400, v138
	v_add_u32_e32 v188, 0x1b800, v138
	v_add_u32_e32 v190, 0x1bc00, v138
	v_add_u32_e32 v191, 0x1c000, v138
	v_readlane_b32 s20, v250, 0
	v_readlane_b32 s24, v250, 4
	v_readlane_b32 s25, v250, 5
	s_mov_b32 s18, 0
	v_readlane_b32 s21, v250, 1
	v_readlane_b32 s22, v250, 2
	v_readlane_b32 s23, v250, 3
	v_readlane_b32 s26, v250, 6
	s_waitcnt vmcnt(16) lgkmcnt(1)
; __device__ __forceinline__ unsigned cvt_pk_bf16(float lo, float hi) { unsigned r; asm volatile("v_cvt_pk_bf16_f32 %0, %1, %2" : "=v"(r) : "v"(lo), "v"(hi)); return r; }
; __device__ __forceinline__ void memattn_tile_lds(const Ctx& C, int pm, int h, unsigned char* lds) {
;     ...
;     for (int mb = 0; mb < 8; ++mb) {
;         f32x16 S = f32x16{};
; #pragma unroll
;         for (int kh = 0; kh < 2; ++kh) {
;             bf16x8 kf[8];
; #pragma unroll
;             for (int k8 = 0; k8 < 8; ++k8) kf[k8] = FRAG(mb * 16 + kh * 8 + k8);
; #pragma unroll
;             for (int k8 = 0; k8 < 8; ++k8) S = __builtin_amdgcn_mfma_f32_32x32x16_bf16(kf[k8], qf[kh * 8 + k8], S, 0, 0, 0);
;         }
;         float p[16];
; #pragma unroll
;         for (int r = 0; r < 16; ++r) { p[r] = __builtin_amdgcn_exp2f(S[r] * c); sum += p[r]; }
;         asm volatile("" : "+v"(sum));
; #pragma unroll
;         for (int s2 = 0; s2 < 2; ++s2)
; #pragma unroll
;             for (int j = 0; j < 4; ++j) pk[mb][s2][j] = cvt_pk_bf16(p[8 * s2 + 2 * j], p[8 * s2 + 2 * j + 1]);
;     }
;     sum += __shfl_xor(sum, 32); const float inv = 1.0f / sum;
;     __syncthreads();
; #pragma unroll 1
;     for (int i0 = 0; i0 < 16; i0 += 8) { u32x4 t[8];
; #pragma unroll
;       for (int i = 0; i < 8; ++i) t[i] = vG[(i0 + i) * 512 + tid];
	v_mfma_f32_32x32x16_bf16 v[0:15], v[0:3], v[96:99], 0
	v_readlane_b32 s27, v250, 7
	s_waitcnt vmcnt(9)
	v_fmac_f32_e32 v25, 0x3b800000, v24
	v_cmp_gt_f32_e32 vcc, s0, v25
	s_waitcnt lgkmcnt(0)
	v_mfma_f32_32x32x16_bf16 v[0:15], v[16:19], v[92:95], v[0:15]
	ds_read_b128 v[16:19], v138 offset:2048
	ds_read_b128 v[20:23], v138 offset:3072
	s_waitcnt lgkmcnt(1)
	v_mfma_f32_32x32x16_bf16 v[0:15], v[16:19], v[88:91], v[0:15]
	s_waitcnt lgkmcnt(0)
	v_mfma_f32_32x32x16_bf16 v[0:15], v[20:23], v[80:83], v[0:15]
	ds_read_b128 v[16:19], v138 offset:4096
	ds_read_b128 v[20:23], v138 offset:5120
	s_waitcnt lgkmcnt(1)
	v_mfma_f32_32x32x16_bf16 v[0:15], v[16:19], v[76:79], v[0:15]
	s_waitcnt lgkmcnt(0)
	v_mfma_f32_32x32x16_bf16 v[0:15], v[20:23], v[72:75], v[0:15]
	ds_read_b128 v[16:19], v138 offset:6144
	ds_read_b128 v[20:23], v138 offset:7168
	s_waitcnt lgkmcnt(1)
	v_mfma_f32_32x32x16_bf16 v[0:15], v[16:19], v[84:87], v[0:15]
	s_waitcnt vmcnt(8) lgkmcnt(0)
	v_mfma_f32_32x32x16_bf16 v[0:15], v[20:23], v[132:135], v[0:15]
	ds_read_b128 v[16:19], v138 offset:8192
	ds_read_b128 v[20:23], v138 offset:9216
	s_waitcnt vmcnt(7) lgkmcnt(1)
	v_mfma_f32_32x32x16_bf16 v[0:15], v[16:19], v[120:123], v[0:15]
	ds_read_b128 v[16:19], v138 offset:10240
	s_waitcnt vmcnt(6) lgkmcnt(1)
	v_mfma_f32_32x32x16_bf16 v[0:15], v[20:23], v[116:119], v[0:15]
	ds_read_b128 v[20:23], v138 offset:11264
	s_waitcnt vmcnt(5) lgkmcnt(1)
	v_mfma_f32_32x32x16_bf16 v[0:15], v[16:19], v[112:115], v[0:15]
	v_mul_f32_e32 v16, 0x4f800000, v25
	v_cndmask_b32_e32 v29, v25, v16, vcc
	ds_read_b128 v[16:19], v138 offset:12288
	ds_read_b128 v[24:27], v138 offset:13312
	v_sqrt_f32_e32 v30, v29
	s_nop 0
	v_add_u32_e32 v31, -1, v30
	s_waitcnt vmcnt(4) lgkmcnt(2)
	v_mfma_f32_32x32x16_bf16 v[0:15], v[20:23], v[108:111], v[0:15]
	ds_read_b128 v[20:23], v138 offset:14336
	v_add_u32_e32 v32, 1, v30
	v_fma_f32 v33, -v31, v30, v29
	v_fma_f32 v34, -v32, v30, v29
	v_cmp_ge_f32_e64 s[0:1], 0, v33
	s_waitcnt vmcnt(3) lgkmcnt(2)
	v_mfma_f32_32x32x16_bf16 v[0:15], v[16:19], v[104:107], v[0:15]
	v_cndmask_b32_e64 v30, v30, v31, s[0:1]
	v_cmp_lt_f32_e64 s[0:1], 0, v34
	s_nop 1
	v_cndmask_b32_e64 v16, v30, v32, s[0:1]
	v_mul_f32_e32 v17, 0x37800000, v16
	v_cndmask_b32_e32 v16, v16, v17, vcc
	s_waitcnt vmcnt(2) lgkmcnt(1)
	v_mfma_f32_32x32x16_bf16 v[0:15], v[24:27], v[100:103], v[0:15]
	v_cmp_class_f32_e32 vcc, v29, v28
	s_nop 1
	v_cndmask_b32_e32 v28, v16, v29, vcc
	ds_read_b128 v[16:19], v138 offset:15360
	v_div_scale_f32 v29, s[0:1], v28, v28, 1.0
	s_waitcnt vmcnt(1) lgkmcnt(1)
	v_mfma_f32_32x32x16_bf16 v[0:15], v[20:23], v[68:71], v[0:15]
	v_rcp_f32_e32 v24, v29
	v_div_scale_f32 v25, vcc, 1.0, v28, 1.0
	s_lshl_b64 s[0:1], s[16:17], 4
	v_fma_f32 v26, -v29, v24, 1.0
	v_fmac_f32_e32 v24, v26, v24
	v_mul_f32_e32 v26, v25, v24
	s_waitcnt vmcnt(0) lgkmcnt(0)
	v_mfma_f32_32x32x16_bf16 v[0:15], v[16:19], v[64:67], v[0:15]
	v_fma_f32 v20, -v29, v26, v25
	v_fmac_f32_e32 v26, v20, v24
	v_fma_f32 v20, -v29, v26, v25
	v_div_fmas_f32 v20, v20, v24, v26
	v_div_fixup_f32 v20, v20, v28, 1.0
	v_mul_f32_e32 v183, 0x3db8aa3b, v20
	s_add_u32 s0, s24, s0
	s_nop 4
	v_mul_f32_e32 v0, v183, v0
	v_mul_f32_e32 v1, v183, v1
	v_exp_f32_e32 v0, v0
	v_mul_f32_e32 v2, v183, v2
	v_exp_f32_e32 v1, v1
	v_mul_f32_e32 v3, v183, v3
	v_exp_f32_e32 v2, v2
	v_mul_f32_e32 v4, v183, v4
	v_exp_f32_e32 v3, v3
	v_mul_f32_e32 v5, v183, v5
	v_exp_f32_e32 v4, v4
	v_add_f32_e32 v16, 0, v0
	v_mul_f32_e32 v6, v183, v6
	v_exp_f32_e32 v5, v5
	v_add_f32_e32 v16, v1, v16
	v_mul_f32_e32 v7, v183, v7
	v_exp_f32_e32 v6, v6
	v_add_f32_e32 v16, v2, v16
	v_mul_f32_e32 v8, v183, v8
	v_exp_f32_e32 v7, v7
	v_add_f32_e32 v16, v3, v16
	v_mul_f32_e32 v9, v183, v9
	v_exp_f32_e32 v8, v8
	v_add_f32_e32 v16, v4, v16
	v_mul_f32_e32 v10, v183, v10
	v_exp_f32_e32 v9, v9
	v_add_f32_e32 v16, v5, v16
	v_mul_f32_e32 v11, v183, v11
	v_exp_f32_e32 v10, v10
	v_add_f32_e32 v16, v6, v16
	v_mul_f32_e32 v12, v183, v12
	v_exp_f32_e32 v11, v11
	v_add_f32_e32 v16, v7, v16
	v_mul_f32_e32 v13, v183, v13
	v_exp_f32_e32 v12, v12
	v_add_f32_e32 v16, v8, v16
	v_mul_f32_e32 v14, v183, v14
	v_exp_f32_e32 v13, v13
	v_add_f32_e32 v16, v9, v16
	v_mul_f32_e32 v15, v183, v15
	v_exp_f32_e32 v14, v14
	v_add_f32_e32 v16, v10, v16
	v_exp_f32_e32 v15, v15
	v_add_f32_e32 v16, v11, v16
	v_add_f32_e32 v16, v12, v16
	v_add_f32_e32 v16, v13, v16
	v_add_f32_e32 v16, v14, v16
	v_add_f32_e32 v32, v15, v16
	v_cvt_pk_bf16_f32 v16, v0, v1
	v_cvt_pk_bf16_f32 v17, v2, v3
	v_cvt_pk_bf16_f32 v18, v4, v5
	v_cvt_pk_bf16_f32 v19, v6, v7
	v_cvt_pk_bf16_f32 v20, v8, v9
	v_cvt_pk_bf16_f32 v21, v10, v11
	v_cvt_pk_bf16_f32 v22, v12, v13
	v_cvt_pk_bf16_f32 v23, v14, v15
	ds_read_b128 v[0:3], v138 offset:16384
	ds_read_b128 v[24:27], v138 offset:17408
	s_waitcnt lgkmcnt(1)
	v_mfma_f32_32x32x16_bf16 v[0:15], v[0:3], v[96:99], 0
	s_addc_u32 s1, s25, s1
	s_add_u32 s0, s0, 0x58d00000
	s_addc_u32 s1, s1, 0
	v_lshlrev_b32_e32 v236, 4, v139
	v_mov_b32_e32 v237, 0
	v_mov_b32_e32 v238, 0x2000
	v_mov_b32_e32 v239, 0
	v_lshl_add_u64 v[236:237], s[0:1], 0, v[236:237]
	global_load_dwordx4 v[204:207], v[236:237], off
	v_lshl_add_u64 v[236:237], v[236:237], 0, v[238:239]
	global_load_dwordx4 v[208:211], v[236:237], off
	v_lshl_add_u64 v[236:237], v[236:237], 0, v[238:239]
	global_load_dwordx4 v[212:215], v[236:237], off
	v_lshl_add_u64 v[236:237], v[236:237], 0, v[238:239]
	global_load_dwordx4 v[216:219], v[236:237], off
	v_lshl_add_u64 v[236:237], v[236:237], 0, v[238:239]
	global_load_dwordx4 v[220:223], v[236:237], off
	v_lshl_add_u64 v[236:237], v[236:237], 0, v[238:239]
	global_load_dwordx4 v[224:227], v[236:237], off
	v_lshl_add_u64 v[236:237], v[236:237], 0, v[238:239]
	global_load_dwordx4 v[228:231], v[236:237], off
	v_lshl_add_u64 v[236:237], v[236:237], 0, v[238:239]
	global_load_dwordx4 v[232:235], v[236:237], off
	v_lshl_add_u64 v[236:237], v[236:237], 0, v[238:239]
	s_mov_b64 s[16:17], -1
	s_waitcnt lgkmcnt(0)
; __device__ __forceinline__ unsigned cvt_pk_bf16(float lo, float hi) { unsigned r; asm volatile("v_cvt_pk_bf16_f32 %0, %1, %2" : "=v"(r) : "v"(lo), "v"(hi)); return r; }
; __device__ __forceinline__ void memattn_tile_lds(const Ctx& C, int pm, int h, unsigned char* lds) {
;     ...
;     for (int mb = 0; mb < 8; ++mb) {
;         f32x16 S = f32x16{};
; #pragma unroll
;         for (int kh = 0; kh < 2; ++kh) {
;             bf16x8 kf[8];
; #pragma unroll
;             for (int k8 = 0; k8 < 8; ++k8) kf[k8] = FRAG(mb * 16 + kh * 8 + k8);
; #pragma unroll
;             for (int k8 = 0; k8 < 8; ++k8) S = __builtin_amdgcn_mfma_f32_32x32x16_bf16(kf[k8], qf[kh * 8 + k8], S, 0, 0, 0);
;         }
;         float p[16];
; #pragma unroll
;         for (int r = 0; r < 16; ++r) { p[r] = __builtin_amdgcn_exp2f(S[r] * c); sum += p[r]; }
;         asm volatile("" : "+v"(sum));
; #pragma unroll
;         for (int s2 = 0; s2 < 2; ++s2)
; #pragma unroll
;             for (int j = 0; j < 4; ++j) pk[mb][s2][j] = cvt_pk_bf16(p[8 * s2 + 2 * j], p[8 * s2 + 2 * j + 1]);
;     }
	v_mfma_f32_32x32x16_bf16 v[0:15], v[24:27], v[92:95], v[0:15]
	ds_read_b128 v[24:27], v138 offset:18432
	ds_read_b128 v[28:31], v138 offset:19456
	s_waitcnt lgkmcnt(1)
	v_mfma_f32_32x32x16_bf16 v[0:15], v[24:27], v[88:91], v[0:15]
	s_waitcnt lgkmcnt(0)
	v_mfma_f32_32x32x16_bf16 v[0:15], v[28:31], v[80:83], v[0:15]
	ds_read_b128 v[24:27], v138 offset:20480
	ds_read_b128 v[28:31], v138 offset:21504
	s_waitcnt lgkmcnt(1)
	v_mfma_f32_32x32x16_bf16 v[0:15], v[24:27], v[76:79], v[0:15]
	s_waitcnt lgkmcnt(0)
	v_mfma_f32_32x32x16_bf16 v[0:15], v[28:31], v[72:75], v[0:15]
	ds_read_b128 v[24:27], v138 offset:22528
	ds_read_b128 v[28:31], v138 offset:23552
	s_waitcnt lgkmcnt(1)
	v_mfma_f32_32x32x16_bf16 v[0:15], v[24:27], v[84:87], v[0:15]
	s_waitcnt lgkmcnt(0)
	v_mfma_f32_32x32x16_bf16 v[0:15], v[28:31], v[132:135], v[0:15]
	ds_read_b128 v[24:27], v138 offset:24576
	ds_read_b128 v[28:31], v138 offset:25600
	s_waitcnt lgkmcnt(1)
	v_mfma_f32_32x32x16_bf16 v[0:15], v[24:27], v[120:123], v[0:15]
	s_waitcnt lgkmcnt(0)
	v_mfma_f32_32x32x16_bf16 v[0:15], v[28:31], v[116:119], v[0:15]
	ds_read_b128 v[24:27], v138 offset:26624
	ds_read_b128 v[28:31], v138 offset:27648
	s_waitcnt lgkmcnt(1)
	v_mfma_f32_32x32x16_bf16 v[0:15], v[24:27], v[112:115], v[0:15]
	s_waitcnt lgkmcnt(0)
	v_mfma_f32_32x32x16_bf16 v[0:15], v[28:31], v[108:111], v[0:15]
	ds_read_b128 v[24:27], v138 offset:28672
	ds_read_b128 v[28:31], v138 offset:29696
	s_waitcnt lgkmcnt(1)
	v_mfma_f32_32x32x16_bf16 v[0:15], v[24:27], v[104:107], v[0:15]
	s_waitcnt lgkmcnt(0)
	v_mfma_f32_32x32x16_bf16 v[0:15], v[28:31], v[100:103], v[0:15]
	ds_read_b128 v[24:27], v138 offset:30720
	ds_read_b128 v[28:31], v138 offset:31744
	s_waitcnt lgkmcnt(1)
	v_mfma_f32_32x32x16_bf16 v[0:15], v[24:27], v[68:71], v[0:15]
	s_waitcnt lgkmcnt(0)
	v_mfma_f32_32x32x16_bf16 v[0:15], v[28:31], v[64:67], v[0:15]
	s_nop 11
	v_mul_f32_e32 v0, v183, v0
	v_mul_f32_e32 v1, v183, v1
	v_exp_f32_e32 v0, v0
	v_mul_f32_e32 v2, v183, v2
	v_exp_f32_e32 v1, v1
	v_mul_f32_e32 v3, v183, v3
	v_exp_f32_e32 v2, v2
	v_mul_f32_e32 v4, v183, v4
	v_exp_f32_e32 v3, v3
	v_mul_f32_e32 v5, v183, v5
	v_exp_f32_e32 v4, v4
	v_add_f32_e32 v24, v32, v0
	v_mul_f32_e32 v6, v183, v6
	v_exp_f32_e32 v5, v5
	v_add_f32_e32 v24, v1, v24
	v_mul_f32_e32 v7, v183, v7
	v_exp_f32_e32 v6, v6
	v_add_f32_e32 v24, v2, v24
	v_mul_f32_e32 v8, v183, v8
	v_exp_f32_e32 v7, v7
	v_add_f32_e32 v24, v3, v24
	v_mul_f32_e32 v9, v183, v9
	v_exp_f32_e32 v8, v8
	v_add_f32_e32 v24, v4, v24
	v_mul_f32_e32 v10, v183, v10
	v_exp_f32_e32 v9, v9
	v_add_f32_e32 v24, v5, v24
	v_mul_f32_e32 v11, v183, v11
	v_exp_f32_e32 v10, v10
	v_add_f32_e32 v24, v6, v24
	v_mul_f32_e32 v12, v183, v12
	v_exp_f32_e32 v11, v11
	v_add_f32_e32 v24, v7, v24
	v_mul_f32_e32 v13, v183, v13
	v_exp_f32_e32 v12, v12
	v_add_f32_e32 v24, v8, v24
	v_mul_f32_e32 v14, v183, v14
	v_exp_f32_e32 v13, v13
	v_add_f32_e32 v24, v9, v24
	v_mul_f32_e32 v15, v183, v15
	v_exp_f32_e32 v14, v14
	v_add_f32_e32 v24, v10, v24
	v_exp_f32_e32 v15, v15
	v_add_f32_e32 v24, v11, v24
	v_add_f32_e32 v24, v12, v24
	v_add_f32_e32 v24, v13, v24
	v_add_f32_e32 v24, v14, v24
	v_add_f32_e32 v40, v15, v24
	v_cvt_pk_bf16_f32 v24, v0, v1
	v_cvt_pk_bf16_f32 v25, v2, v3
	v_cvt_pk_bf16_f32 v26, v4, v5
	v_cvt_pk_bf16_f32 v27, v6, v7
	v_cvt_pk_bf16_f32 v28, v8, v9
	v_cvt_pk_bf16_f32 v29, v10, v11
	v_cvt_pk_bf16_f32 v30, v12, v13
	v_cvt_pk_bf16_f32 v31, v14, v15
	ds_read_b128 v[0:3], v138 offset:32768
	ds_read_b128 v[32:35], v138 offset:33792
	s_waitcnt lgkmcnt(1)
	v_mfma_f32_32x32x16_bf16 v[0:15], v[0:3], v[96:99], 0
	s_waitcnt lgkmcnt(0)
	v_mfma_f32_32x32x16_bf16 v[0:15], v[32:35], v[92:95], v[0:15]
	ds_read_b128 v[32:35], v138 offset:34816
	ds_read_b128 v[36:39], v138 offset:35840
	s_waitcnt lgkmcnt(1)
	v_mfma_f32_32x32x16_bf16 v[0:15], v[32:35], v[88:91], v[0:15]
	s_waitcnt lgkmcnt(0)
	v_mfma_f32_32x32x16_bf16 v[0:15], v[36:39], v[80:83], v[0:15]
	ds_read_b128 v[32:35], v138 offset:36864
	ds_read_b128 v[36:39], v138 offset:37888
	s_waitcnt lgkmcnt(1)
	v_mfma_f32_32x32x16_bf16 v[0:15], v[32:35], v[76:79], v[0:15]
	s_waitcnt lgkmcnt(0)
	v_mfma_f32_32x32x16_bf16 v[0:15], v[36:39], v[72:75], v[0:15]
	ds_read_b128 v[32:35], v138 offset:38912
	ds_read_b128 v[36:39], v138 offset:39936
	s_waitcnt lgkmcnt(1)
	v_mfma_f32_32x32x16_bf16 v[0:15], v[32:35], v[84:87], v[0:15]
	s_waitcnt lgkmcnt(0)
	v_mfma_f32_32x32x16_bf16 v[0:15], v[36:39], v[132:135], v[0:15]
	ds_read_b128 v[32:35], v138 offset:40960
	ds_read_b128 v[36:39], v138 offset:41984
	s_waitcnt lgkmcnt(1)
	v_mfma_f32_32x32x16_bf16 v[0:15], v[32:35], v[120:123], v[0:15]
	s_waitcnt lgkmcnt(0)
	v_mfma_f32_32x32x16_bf16 v[0:15], v[36:39], v[116:119], v[0:15]
	ds_read_b128 v[32:35], v138 offset:43008
	ds_read_b128 v[36:39], v138 offset:44032
	s_waitcnt lgkmcnt(1)
	v_mfma_f32_32x32x16_bf16 v[0:15], v[32:35], v[112:115], v[0:15]
	s_waitcnt lgkmcnt(0)
	v_mfma_f32_32x32x16_bf16 v[0:15], v[36:39], v[108:111], v[0:15]
	ds_read_b128 v[32:35], v138 offset:45056
	ds_read_b128 v[36:39], v138 offset:46080
	s_waitcnt lgkmcnt(1)
	v_mfma_f32_32x32x16_bf16 v[0:15], v[32:35], v[104:107], v[0:15]
	s_waitcnt lgkmcnt(0)
	v_mfma_f32_32x32x16_bf16 v[0:15], v[36:39], v[100:103], v[0:15]
	ds_read_b128 v[32:35], v138 offset:47104
	ds_read_b128 v[36:39], v138 offset:48128
	s_waitcnt lgkmcnt(1)
	v_mfma_f32_32x32x16_bf16 v[0:15], v[32:35], v[68:71], v[0:15]
	s_waitcnt lgkmcnt(0)
; __device__ __forceinline__ unsigned cvt_pk_bf16(float lo, float hi) { unsigned r; asm volatile("v_cvt_pk_bf16_f32 %0, %1, %2" : "=v"(r) : "v"(lo), "v"(hi)); return r; }
; __device__ __forceinline__ void memattn_tile_lds(const Ctx& C, int pm, int h, unsigned char* lds) {
;     ...
;     for (int mb = 0; mb < 8; ++mb) {
;         f32x16 S = f32x16{};
; #pragma unroll
;         for (int kh = 0; kh < 2; ++kh) {
;             bf16x8 kf[8];
; #pragma unroll
;             for (int k8 = 0; k8 < 8; ++k8) kf[k8] = FRAG(mb * 16 + kh * 8 + k8);
; #pragma unroll
;             for (int k8 = 0; k8 < 8; ++k8) S = __builtin_amdgcn_mfma_f32_32x32x16_bf16(kf[k8], qf[kh * 8 + k8], S, 0, 0, 0);
;         }
;         float p[16];
; #pragma unroll
;         for (int r = 0; r < 16; ++r) { p[r] = __builtin_amdgcn_exp2f(S[r] * c); sum += p[r]; }
;         asm volatile("" : "+v"(sum));
; #pragma unroll
;         for (int s2 = 0; s2 < 2; ++s2)
; #pragma unroll
;             for (int j = 0; j < 4; ++j) pk[mb][s2][j] = cvt_pk_bf16(p[8 * s2 + 2 * j], p[8 * s2 + 2 * j + 1]);
;     }
	v_mfma_f32_32x32x16_bf16 v[0:15], v[36:39], v[64:67], v[0:15]
	s_nop 11
	v_mul_f32_e32 v0, v183, v0
	v_mul_f32_e32 v1, v183, v1
	v_exp_f32_e32 v0, v0
	v_mul_f32_e32 v2, v183, v2
	v_exp_f32_e32 v1, v1
	v_mul_f32_e32 v3, v183, v3
	v_exp_f32_e32 v2, v2
	v_mul_f32_e32 v4, v183, v4
	v_exp_f32_e32 v3, v3
	v_mul_f32_e32 v5, v183, v5
	v_exp_f32_e32 v4, v4
	v_add_f32_e32 v32, v40, v0
	v_mul_f32_e32 v6, v183, v6
	v_exp_f32_e32 v5, v5
	v_add_f32_e32 v32, v1, v32
	v_mul_f32_e32 v7, v183, v7
	v_exp_f32_e32 v6, v6
	v_add_f32_e32 v32, v2, v32
	v_mul_f32_e32 v8, v183, v8
	v_exp_f32_e32 v7, v7
	v_add_f32_e32 v32, v3, v32
	v_mul_f32_e32 v9, v183, v9
	v_exp_f32_e32 v8, v8
	v_add_f32_e32 v32, v4, v32
	v_mul_f32_e32 v10, v183, v10
	v_exp_f32_e32 v9, v9
	v_add_f32_e32 v32, v5, v32
	v_mul_f32_e32 v11, v183, v11
	v_exp_f32_e32 v10, v10
	v_add_f32_e32 v32, v6, v32
	v_mul_f32_e32 v12, v183, v12
	v_exp_f32_e32 v11, v11
	v_add_f32_e32 v32, v7, v32
	v_mul_f32_e32 v13, v183, v13
	v_exp_f32_e32 v12, v12
	v_add_f32_e32 v32, v8, v32
	v_mul_f32_e32 v14, v183, v14
	v_exp_f32_e32 v13, v13
	v_add_f32_e32 v32, v9, v32
	v_mul_f32_e32 v15, v183, v15
	v_exp_f32_e32 v14, v14
	v_add_f32_e32 v32, v10, v32
	v_exp_f32_e32 v15, v15
	v_add_f32_e32 v32, v11, v32
	v_add_f32_e32 v32, v12, v32
	v_add_f32_e32 v32, v13, v32
	v_add_f32_e32 v32, v14, v32
	v_add_f32_e32 v48, v15, v32
	v_cvt_pk_bf16_f32 v32, v0, v1
	v_cvt_pk_bf16_f32 v33, v2, v3
	v_cvt_pk_bf16_f32 v34, v4, v5
	v_cvt_pk_bf16_f32 v35, v6, v7
	v_cvt_pk_bf16_f32 v36, v8, v9
	v_cvt_pk_bf16_f32 v37, v10, v11
	v_cvt_pk_bf16_f32 v38, v12, v13
	v_cvt_pk_bf16_f32 v39, v14, v15
	ds_read_b128 v[0:3], v138 offset:49152
	ds_read_b128 v[40:43], v138 offset:50176
	s_waitcnt lgkmcnt(1)
	v_mfma_f32_32x32x16_bf16 v[0:15], v[0:3], v[96:99], 0
	s_waitcnt lgkmcnt(0)
	v_mfma_f32_32x32x16_bf16 v[0:15], v[40:43], v[92:95], v[0:15]
	ds_read_b128 v[40:43], v138 offset:51200
	ds_read_b128 v[44:47], v138 offset:52224
	s_waitcnt lgkmcnt(1)
	v_mfma_f32_32x32x16_bf16 v[0:15], v[40:43], v[88:91], v[0:15]
	s_waitcnt lgkmcnt(0)
	v_mfma_f32_32x32x16_bf16 v[0:15], v[44:47], v[80:83], v[0:15]
	ds_read_b128 v[40:43], v138 offset:53248
	ds_read_b128 v[44:47], v138 offset:54272
	s_waitcnt lgkmcnt(1)
	v_mfma_f32_32x32x16_bf16 v[0:15], v[40:43], v[76:79], v[0:15]
	s_waitcnt lgkmcnt(0)
	v_mfma_f32_32x32x16_bf16 v[0:15], v[44:47], v[72:75], v[0:15]
	ds_read_b128 v[40:43], v138 offset:55296
	ds_read_b128 v[44:47], v138 offset:56320
	s_waitcnt lgkmcnt(1)
	v_mfma_f32_32x32x16_bf16 v[0:15], v[40:43], v[84:87], v[0:15]
	s_waitcnt lgkmcnt(0)
	v_mfma_f32_32x32x16_bf16 v[0:15], v[44:47], v[132:135], v[0:15]
	ds_read_b128 v[40:43], v138 offset:57344
	ds_read_b128 v[44:47], v138 offset:58368
	s_waitcnt lgkmcnt(1)
	v_mfma_f32_32x32x16_bf16 v[0:15], v[40:43], v[120:123], v[0:15]
	s_waitcnt lgkmcnt(0)
	v_mfma_f32_32x32x16_bf16 v[0:15], v[44:47], v[116:119], v[0:15]
	ds_read_b128 v[40:43], v138 offset:59392
	ds_read_b128 v[44:47], v138 offset:60416
	s_waitcnt lgkmcnt(1)
	v_mfma_f32_32x32x16_bf16 v[0:15], v[40:43], v[112:115], v[0:15]
	s_waitcnt lgkmcnt(0)
	v_mfma_f32_32x32x16_bf16 v[0:15], v[44:47], v[108:111], v[0:15]
	ds_read_b128 v[40:43], v138 offset:61440
	ds_read_b128 v[44:47], v138 offset:62464
	s_waitcnt lgkmcnt(1)
	v_mfma_f32_32x32x16_bf16 v[0:15], v[40:43], v[104:107], v[0:15]
	s_waitcnt lgkmcnt(0)
	v_mfma_f32_32x32x16_bf16 v[0:15], v[44:47], v[100:103], v[0:15]
	ds_read_b128 v[40:43], v138 offset:63488
	ds_read_b128 v[44:47], v138 offset:64512
	s_waitcnt lgkmcnt(1)
	v_mfma_f32_32x32x16_bf16 v[0:15], v[40:43], v[68:71], v[0:15]
	s_waitcnt lgkmcnt(0)
	v_mfma_f32_32x32x16_bf16 v[0:15], v[44:47], v[64:67], v[0:15]
	s_nop 11
	v_mul_f32_e32 v0, v183, v0
	v_mul_f32_e32 v1, v183, v1
	v_exp_f32_e32 v0, v0
	v_mul_f32_e32 v2, v183, v2
	v_exp_f32_e32 v1, v1
	v_mul_f32_e32 v3, v183, v3
	v_exp_f32_e32 v2, v2
	v_mul_f32_e32 v4, v183, v4
	v_exp_f32_e32 v3, v3
	v_mul_f32_e32 v5, v183, v5
	v_exp_f32_e32 v4, v4
	v_add_f32_e32 v40, v48, v0
	v_mul_f32_e32 v6, v183, v6
	v_exp_f32_e32 v5, v5
	v_add_f32_e32 v40, v1, v40
	v_mul_f32_e32 v7, v183, v7
	v_exp_f32_e32 v6, v6
	v_add_f32_e32 v40, v2, v40
	v_mul_f32_e32 v8, v183, v8
	v_exp_f32_e32 v7, v7
	v_add_f32_e32 v40, v3, v40
	v_mul_f32_e32 v9, v183, v9
	v_exp_f32_e32 v8, v8
	v_add_f32_e32 v40, v4, v40
	v_mul_f32_e32 v10, v183, v10
	v_exp_f32_e32 v9, v9
	v_add_f32_e32 v40, v5, v40
	v_mul_f32_e32 v11, v183, v11
	v_exp_f32_e32 v10, v10
	v_add_f32_e32 v40, v6, v40
	v_mul_f32_e32 v12, v183, v12
	v_exp_f32_e32 v11, v11
	v_add_f32_e32 v40, v7, v40
	v_mul_f32_e32 v13, v183, v13
	v_exp_f32_e32 v12, v12
	v_add_f32_e32 v40, v8, v40
	v_mul_f32_e32 v14, v183, v14
	v_exp_f32_e32 v13, v13
	v_add_f32_e32 v40, v9, v40
	v_mul_f32_e32 v15, v183, v15
	v_exp_f32_e32 v14, v14
	v_add_f32_e32 v40, v10, v40
	v_exp_f32_e32 v15, v15
	v_add_f32_e32 v40, v11, v40
	v_add_f32_e32 v40, v12, v40
	v_add_f32_e32 v40, v13, v40
	v_add_f32_e32 v40, v14, v40
	v_add_f32_e32 v56, v15, v40
	v_cvt_pk_bf16_f32 v40, v0, v1
	v_cvt_pk_bf16_f32 v41, v2, v3
	v_cvt_pk_bf16_f32 v42, v4, v5
	v_cvt_pk_bf16_f32 v43, v6, v7
	v_cvt_pk_bf16_f32 v44, v8, v9
	v_cvt_pk_bf16_f32 v45, v10, v11
	v_cvt_pk_bf16_f32 v46, v12, v13
	v_cvt_pk_bf16_f32 v47, v14, v15
	ds_read_b128 v[0:3], v142
	ds_read_b128 v[48:51], v143
	s_waitcnt lgkmcnt(1)
	v_mfma_f32_32x32x16_bf16 v[0:15], v[0:3], v[96:99], 0
	ds_read_b128 v[52:55], v146
	s_waitcnt lgkmcnt(1)
	v_mfma_f32_32x32x16_bf16 v[0:15], v[48:51], v[92:95], v[0:15]
	ds_read_b128 v[48:51], v144
	s_waitcnt lgkmcnt(0)
	v_mfma_f32_32x32x16_bf16 v[0:15], v[48:51], v[88:91], v[0:15]
	ds_read_b128 v[48:51], v145
	v_mfma_f32_32x32x16_bf16 v[0:15], v[52:55], v[80:83], v[0:15]
	ds_read_b128 v[52:55], v148
	s_waitcnt lgkmcnt(1)
; __device__ __forceinline__ unsigned cvt_pk_bf16(float lo, float hi) { unsigned r; asm volatile("v_cvt_pk_bf16_f32 %0, %1, %2" : "=v"(r) : "v"(lo), "v"(hi)); return r; }
; __device__ __forceinline__ void memattn_tile_lds(const Ctx& C, int pm, int h, unsigned char* lds) {
;     ...
;     for (int mb = 0; mb < 8; ++mb) {
;         f32x16 S = f32x16{};
; #pragma unroll
;         for (int kh = 0; kh < 2; ++kh) {
;             bf16x8 kf[8];
; #pragma unroll
;             for (int k8 = 0; k8 < 8; ++k8) kf[k8] = FRAG(mb * 16 + kh * 8 + k8);
; #pragma unroll
;             for (int k8 = 0; k8 < 8; ++k8) S = __builtin_amdgcn_mfma_f32_32x32x16_bf16(kf[k8], qf[kh * 8 + k8], S, 0, 0, 0);
;         }
;         float p[16];
; #pragma unroll
;         for (int r = 0; r < 16; ++r) { p[r] = __builtin_amdgcn_exp2f(S[r] * c); sum += p[r]; }
;         asm volatile("" : "+v"(sum));
; #pragma unroll
;         for (int s2 = 0; s2 < 2; ++s2)
; #pragma unroll
;             for (int j = 0; j < 4; ++j) pk[mb][s2][j] = cvt_pk_bf16(p[8 * s2 + 2 * j], p[8 * s2 + 2 * j + 1]);
;     }
	v_mfma_f32_32x32x16_bf16 v[0:15], v[48:51], v[76:79], v[0:15]
	ds_read_b128 v[48:51], v147
	s_waitcnt lgkmcnt(1)
	v_mfma_f32_32x32x16_bf16 v[0:15], v[52:55], v[72:75], v[0:15]
	ds_read_b128 v[52:55], v149
	s_waitcnt lgkmcnt(1)
	v_mfma_f32_32x32x16_bf16 v[0:15], v[48:51], v[84:87], v[0:15]
	ds_read_b128 v[48:51], v150
	s_waitcnt lgkmcnt(1)
	v_mfma_f32_32x32x16_bf16 v[0:15], v[52:55], v[132:135], v[0:15]
	ds_read_b128 v[52:55], v151
	s_waitcnt lgkmcnt(1)
	v_mfma_f32_32x32x16_bf16 v[0:15], v[48:51], v[120:123], v[0:15]
	ds_read_b128 v[48:51], v152
	s_waitcnt lgkmcnt(1)
	v_mfma_f32_32x32x16_bf16 v[0:15], v[52:55], v[116:119], v[0:15]
	ds_read_b128 v[52:55], v154
	s_waitcnt lgkmcnt(1)
	v_mfma_f32_32x32x16_bf16 v[0:15], v[48:51], v[112:115], v[0:15]
	ds_read_b128 v[48:51], v153
	s_waitcnt lgkmcnt(1)
	v_mfma_f32_32x32x16_bf16 v[0:15], v[52:55], v[108:111], v[0:15]
	ds_read_b128 v[52:55], v156
	s_waitcnt lgkmcnt(1)
	v_mfma_f32_32x32x16_bf16 v[0:15], v[48:51], v[104:107], v[0:15]
	ds_read_b128 v[48:51], v155
	s_waitcnt lgkmcnt(1)
	v_mfma_f32_32x32x16_bf16 v[0:15], v[52:55], v[100:103], v[0:15]
	ds_read_b128 v[52:55], v157
	s_waitcnt lgkmcnt(1)
	v_mfma_f32_32x32x16_bf16 v[0:15], v[48:51], v[68:71], v[0:15]
	s_waitcnt lgkmcnt(0)
	v_mfma_f32_32x32x16_bf16 v[0:15], v[52:55], v[64:67], v[0:15]
	s_nop 11
	v_mul_f32_e32 v0, v183, v0
	v_mul_f32_e32 v1, v183, v1
	v_exp_f32_e32 v0, v0
	v_mul_f32_e32 v2, v183, v2
	v_exp_f32_e32 v1, v1
	v_mul_f32_e32 v3, v183, v3
	v_exp_f32_e32 v2, v2
	v_mul_f32_e32 v4, v183, v4
	v_exp_f32_e32 v3, v3
	v_mul_f32_e32 v5, v183, v5
	v_exp_f32_e32 v4, v4
	v_add_f32_e32 v48, v56, v0
	v_mul_f32_e32 v6, v183, v6
	v_exp_f32_e32 v5, v5
	v_add_f32_e32 v48, v1, v48
	v_mul_f32_e32 v7, v183, v7
	v_exp_f32_e32 v6, v6
	v_add_f32_e32 v48, v2, v48
	v_mul_f32_e32 v8, v183, v8
	v_exp_f32_e32 v7, v7
	v_add_f32_e32 v48, v3, v48
	v_mul_f32_e32 v9, v183, v9
	v_exp_f32_e32 v8, v8
	v_add_f32_e32 v48, v4, v48
	v_mul_f32_e32 v10, v183, v10
	v_exp_f32_e32 v9, v9
	v_add_f32_e32 v48, v5, v48
	v_mul_f32_e32 v11, v183, v11
	v_exp_f32_e32 v10, v10
	v_add_f32_e32 v48, v6, v48
	v_mul_f32_e32 v12, v183, v12
	v_exp_f32_e32 v11, v11
	v_add_f32_e32 v48, v7, v48
	v_mul_f32_e32 v13, v183, v13
	v_exp_f32_e32 v12, v12
	v_add_f32_e32 v48, v8, v48
	v_mul_f32_e32 v14, v183, v14
	v_exp_f32_e32 v13, v13
	v_add_f32_e32 v48, v9, v48
	v_mul_f32_e32 v15, v183, v15
	v_exp_f32_e32 v14, v14
	v_add_f32_e32 v48, v10, v48
	v_exp_f32_e32 v15, v15
	v_add_f32_e32 v48, v11, v48
	v_add_f32_e32 v48, v12, v48
	v_add_f32_e32 v48, v13, v48
	v_add_f32_e32 v48, v14, v48
	v_add_f32_e32 v124, v15, v48
	v_cvt_pk_bf16_f32 v48, v0, v1
	v_cvt_pk_bf16_f32 v49, v2, v3
	v_cvt_pk_bf16_f32 v50, v4, v5
	v_cvt_pk_bf16_f32 v51, v6, v7
	v_cvt_pk_bf16_f32 v52, v8, v9
	v_cvt_pk_bf16_f32 v53, v10, v11
	v_cvt_pk_bf16_f32 v54, v12, v13
	v_cvt_pk_bf16_f32 v55, v14, v15
	ds_read_b128 v[0:3], v158
	ds_read_b128 v[56:59], v159
	s_waitcnt lgkmcnt(1)
	v_mfma_f32_32x32x16_bf16 v[0:15], v[0:3], v[96:99], 0
	ds_read_b128 v[60:63], v162
	s_waitcnt lgkmcnt(1)
	v_mfma_f32_32x32x16_bf16 v[0:15], v[56:59], v[92:95], v[0:15]
	ds_read_b128 v[56:59], v160
	s_waitcnt lgkmcnt(0)
	v_mfma_f32_32x32x16_bf16 v[0:15], v[56:59], v[88:91], v[0:15]
	ds_read_b128 v[56:59], v161
	v_mfma_f32_32x32x16_bf16 v[0:15], v[60:63], v[80:83], v[0:15]
	ds_read_b128 v[60:63], v164
	s_waitcnt lgkmcnt(1)
	v_mfma_f32_32x32x16_bf16 v[0:15], v[56:59], v[76:79], v[0:15]
	ds_read_b128 v[56:59], v163
	s_waitcnt lgkmcnt(1)
	v_mfma_f32_32x32x16_bf16 v[0:15], v[60:63], v[72:75], v[0:15]
	ds_read_b128 v[60:63], v165
	s_waitcnt lgkmcnt(1)
	v_mfma_f32_32x32x16_bf16 v[0:15], v[56:59], v[84:87], v[0:15]
	ds_read_b128 v[56:59], v166
	s_waitcnt lgkmcnt(1)
	v_mfma_f32_32x32x16_bf16 v[0:15], v[60:63], v[132:135], v[0:15]
	ds_read_b128 v[60:63], v167
	s_waitcnt lgkmcnt(1)
	v_mfma_f32_32x32x16_bf16 v[0:15], v[56:59], v[120:123], v[0:15]
	ds_read_b128 v[56:59], v168
	s_waitcnt lgkmcnt(1)
	v_mfma_f32_32x32x16_bf16 v[0:15], v[60:63], v[116:119], v[0:15]
	ds_read_b128 v[60:63], v170
	s_waitcnt lgkmcnt(1)
	v_mfma_f32_32x32x16_bf16 v[0:15], v[56:59], v[112:115], v[0:15]
	ds_read_b128 v[56:59], v169
	s_waitcnt lgkmcnt(1)
	v_mfma_f32_32x32x16_bf16 v[0:15], v[60:63], v[108:111], v[0:15]
	ds_read_b128 v[60:63], v172
	s_waitcnt lgkmcnt(1)
	v_mfma_f32_32x32x16_bf16 v[0:15], v[56:59], v[104:107], v[0:15]
	ds_read_b128 v[56:59], v171
	s_waitcnt lgkmcnt(1)
	v_mfma_f32_32x32x16_bf16 v[0:15], v[60:63], v[100:103], v[0:15]
	ds_read_b128 v[60:63], v173
	s_waitcnt lgkmcnt(1)
	v_mfma_f32_32x32x16_bf16 v[0:15], v[56:59], v[68:71], v[0:15]
	s_waitcnt lgkmcnt(0)
	v_mfma_f32_32x32x16_bf16 v[0:15], v[60:63], v[64:67], v[0:15]
	s_nop 11
	v_mul_f32_e32 v0, v183, v0
	v_mul_f32_e32 v1, v183, v1
	v_exp_f32_e32 v0, v0
	v_mul_f32_e32 v2, v183, v2
	v_exp_f32_e32 v1, v1
	v_mul_f32_e32 v3, v183, v3
	v_exp_f32_e32 v2, v2
	v_mul_f32_e32 v4, v183, v4
	v_exp_f32_e32 v3, v3
	v_mul_f32_e32 v5, v183, v5
	v_exp_f32_e32 v4, v4
	v_add_f32_e32 v56, v124, v0
	v_mul_f32_e32 v6, v183, v6
	v_exp_f32_e32 v5, v5
	v_add_f32_e32 v56, v1, v56
	v_mul_f32_e32 v7, v183, v7
	v_exp_f32_e32 v6, v6
	v_add_f32_e32 v56, v2, v56
	v_mul_f32_e32 v8, v183, v8
	v_exp_f32_e32 v7, v7
	v_add_f32_e32 v56, v3, v56
	v_mul_f32_e32 v9, v183, v9
	v_exp_f32_e32 v8, v8
	v_add_f32_e32 v56, v4, v56
	v_mul_f32_e32 v10, v183, v10
	v_exp_f32_e32 v9, v9
	v_add_f32_e32 v56, v5, v56
	v_mul_f32_e32 v11, v183, v11
	v_exp_f32_e32 v10, v10
	v_add_f32_e32 v56, v6, v56
	v_mul_f32_e32 v12, v183, v12
	v_exp_f32_e32 v11, v11
	v_add_f32_e32 v56, v7, v56
	v_mul_f32_e32 v13, v183, v13
	v_exp_f32_e32 v12, v12
	v_add_f32_e32 v56, v8, v56
	v_mul_f32_e32 v14, v183, v14
	v_exp_f32_e32 v13, v13
	v_add_f32_e32 v56, v9, v56
	v_mul_f32_e32 v15, v183, v15
	v_exp_f32_e32 v14, v14
	v_add_f32_e32 v56, v10, v56
	v_exp_f32_e32 v15, v15
	v_add_f32_e32 v56, v11, v56
	v_add_f32_e32 v56, v12, v56
	v_add_f32_e32 v56, v13, v56
	v_add_f32_e32 v56, v14, v56
	v_add_f32_e32 v192, v15, v56
	v_cvt_pk_bf16_f32 v56, v0, v1
	v_cvt_pk_bf16_f32 v57, v2, v3
	v_cvt_pk_bf16_f32 v58, v4, v5
	v_cvt_pk_bf16_f32 v59, v6, v7
	v_cvt_pk_bf16_f32 v60, v8, v9
	v_cvt_pk_bf16_f32 v61, v10, v11
	v_cvt_pk_bf16_f32 v62, v12, v13
	v_cvt_pk_bf16_f32 v63, v14, v15
	ds_read_b128 v[0:3], v174
	ds_read_b128 v[124:127], v175
	s_waitcnt lgkmcnt(1)
; __device__ __forceinline__ unsigned cvt_pk_bf16(float lo, float hi) { unsigned r; asm volatile("v_cvt_pk_bf16_f32 %0, %1, %2" : "=v"(r) : "v"(lo), "v"(hi)); return r; }
; __device__ __forceinline__ void memattn_tile_lds(const Ctx& C, int pm, int h, unsigned char* lds) {
;     ...
;     for (int mb = 0; mb < 8; ++mb) {
;         f32x16 S = f32x16{};
; #pragma unroll
;         for (int kh = 0; kh < 2; ++kh) {
;             bf16x8 kf[8];
; #pragma unroll
;             for (int k8 = 0; k8 < 8; ++k8) kf[k8] = FRAG(mb * 16 + kh * 8 + k8);
; #pragma unroll
;             for (int k8 = 0; k8 < 8; ++k8) S = __builtin_amdgcn_mfma_f32_32x32x16_bf16(kf[k8], qf[kh * 8 + k8], S, 0, 0, 0);
;         }
;         float p[16];
; #pragma unroll
;         for (int r = 0; r < 16; ++r) { p[r] = __builtin_amdgcn_exp2f(S[r] * c); sum += p[r]; }
;         asm volatile("" : "+v"(sum));
; #pragma unroll
;         for (int s2 = 0; s2 < 2; ++s2)
; #pragma unroll
;             for (int j = 0; j < 4; ++j) pk[mb][s2][j] = cvt_pk_bf16(p[8 * s2 + 2 * j], p[8 * s2 + 2 * j + 1]);
;     }
	v_mfma_f32_32x32x16_bf16 v[0:15], v[0:3], v[96:99], 0
	ds_read_b128 v[128:131], v178
	s_waitcnt lgkmcnt(1)
	v_mfma_f32_32x32x16_bf16 v[0:15], v[124:127], v[92:95], v[0:15]
	ds_read_b128 v[124:127], v176
	s_waitcnt lgkmcnt(0)
	v_mfma_f32_32x32x16_bf16 v[0:15], v[124:127], v[88:91], v[0:15]
	ds_read_b128 v[124:127], v177
	v_mfma_f32_32x32x16_bf16 v[0:15], v[128:131], v[80:83], v[0:15]
	ds_read_b128 v[128:131], v180
	s_waitcnt lgkmcnt(1)
	v_mfma_f32_32x32x16_bf16 v[0:15], v[124:127], v[76:79], v[0:15]
	ds_read_b128 v[124:127], v179
	s_waitcnt lgkmcnt(1)
	v_mfma_f32_32x32x16_bf16 v[0:15], v[128:131], v[72:75], v[0:15]
	ds_read_b128 v[128:131], v181
	s_waitcnt lgkmcnt(1)
	v_mfma_f32_32x32x16_bf16 v[0:15], v[124:127], v[84:87], v[0:15]
	ds_read_b128 v[124:127], v182
	s_waitcnt lgkmcnt(1)
	v_mfma_f32_32x32x16_bf16 v[0:15], v[128:131], v[132:135], v[0:15]
	ds_read_b128 v[128:131], v184
	s_waitcnt lgkmcnt(1)
	v_mfma_f32_32x32x16_bf16 v[0:15], v[124:127], v[120:123], v[0:15]
	ds_read_b128 v[124:127], v185
	s_waitcnt lgkmcnt(1)
	v_mfma_f32_32x32x16_bf16 v[0:15], v[128:131], v[116:119], v[0:15]
	ds_read_b128 v[128:131], v187
	s_waitcnt lgkmcnt(1)
	v_mfma_f32_32x32x16_bf16 v[0:15], v[124:127], v[112:115], v[0:15]
	ds_read_b128 v[124:127], v186
	s_waitcnt lgkmcnt(1)
	v_mfma_f32_32x32x16_bf16 v[0:15], v[128:131], v[108:111], v[0:15]
	ds_read_b128 v[128:131], v189
	s_waitcnt lgkmcnt(1)
	v_mfma_f32_32x32x16_bf16 v[0:15], v[124:127], v[104:107], v[0:15]
	ds_read_b128 v[124:127], v188
	s_waitcnt lgkmcnt(1)
	v_mfma_f32_32x32x16_bf16 v[0:15], v[128:131], v[100:103], v[0:15]
	ds_read_b128 v[128:131], v190
	s_waitcnt lgkmcnt(1)
	v_mfma_f32_32x32x16_bf16 v[0:15], v[124:127], v[68:71], v[0:15]
	s_waitcnt lgkmcnt(0)
	v_mfma_f32_32x32x16_bf16 v[0:15], v[128:131], v[64:67], v[0:15]
	s_nop 11
	v_mul_f32_e32 v0, v183, v0
	v_mul_f32_e32 v1, v183, v1
	v_exp_f32_e32 v0, v0
	v_mul_f32_e32 v2, v183, v2
	v_exp_f32_e32 v1, v1
	v_mul_f32_e32 v3, v183, v3
	v_exp_f32_e32 v2, v2
	v_mul_f32_e32 v4, v183, v4
	v_exp_f32_e32 v3, v3
	v_mul_f32_e32 v5, v183, v5
	v_exp_f32_e32 v4, v4
	v_add_f32_e32 v124, v192, v0
	v_mul_f32_e32 v6, v183, v6
	v_exp_f32_e32 v5, v5
	v_add_f32_e32 v124, v1, v124
	v_mul_f32_e32 v7, v183, v7
	v_exp_f32_e32 v6, v6
	v_add_f32_e32 v124, v2, v124
	v_mul_f32_e32 v8, v183, v8
	v_exp_f32_e32 v7, v7
	v_add_f32_e32 v124, v3, v124
	v_mul_f32_e32 v9, v183, v9
	v_exp_f32_e32 v8, v8
	v_add_f32_e32 v124, v4, v124
	v_mul_f32_e32 v10, v183, v10
	v_exp_f32_e32 v9, v9
	v_add_f32_e32 v124, v5, v124
	v_mul_f32_e32 v11, v183, v11
	v_exp_f32_e32 v10, v10
	v_add_f32_e32 v124, v6, v124
	v_mul_f32_e32 v12, v183, v12
	v_exp_f32_e32 v11, v11
	v_add_f32_e32 v124, v7, v124
	v_mul_f32_e32 v13, v183, v13
	v_exp_f32_e32 v12, v12
	v_add_f32_e32 v124, v8, v124
	v_mul_f32_e32 v14, v183, v14
	v_exp_f32_e32 v13, v13
	v_add_f32_e32 v124, v9, v124
	v_mul_f32_e32 v15, v183, v15
	v_exp_f32_e32 v14, v14
	v_add_f32_e32 v124, v10, v124
	v_exp_f32_e32 v15, v15
	v_add_f32_e32 v124, v11, v124
	v_add_f32_e32 v124, v12, v124
	v_add_f32_e32 v124, v13, v124
	v_add_f32_e32 v124, v14, v124
	v_add_f32_e32 v193, v15, v124
	v_cvt_pk_bf16_f32 v124, v0, v1
	v_cvt_pk_bf16_f32 v125, v2, v3
	v_cvt_pk_bf16_f32 v126, v4, v5
	v_cvt_pk_bf16_f32 v127, v6, v7
	v_cvt_pk_bf16_f32 v128, v8, v9
	v_cvt_pk_bf16_f32 v129, v10, v11
	v_cvt_pk_bf16_f32 v130, v12, v13
	v_cvt_pk_bf16_f32 v131, v14, v15
	ds_read_b128 v[0:3], v191
	v_add_u32_e32 v192, 0x1c400, v138
	ds_read_b128 v[194:197], v192
	s_waitcnt lgkmcnt(1)
	v_mfma_f32_32x32x16_bf16 v[0:15], v[0:3], v[96:99], 0
	v_add_u32_e32 v96, 0x1c800, v138
	s_waitcnt lgkmcnt(0)
	v_mfma_f32_32x32x16_bf16 v[0:15], v[194:197], v[92:95], v[0:15]
	ds_read_b128 v[194:197], v96
	v_add_u32_e32 v92, 0x1cc00, v138
	ds_read_b128 v[198:201], v92
	s_waitcnt lgkmcnt(1)
	v_mfma_f32_32x32x16_bf16 v[0:15], v[194:197], v[88:91], v[0:15]
	v_add_u32_e32 v88, 0x1d000, v138
	ds_read_b128 v[194:197], v88
	s_waitcnt lgkmcnt(1)
	v_mfma_f32_32x32x16_bf16 v[0:15], v[198:201], v[80:83], v[0:15]
	v_add_u32_e32 v80, 0x1d400, v138
	ds_read_b128 v[198:201], v80
	v_add_u32_e32 v81, 0x1ec00, v138
	s_waitcnt lgkmcnt(1)
	v_mfma_f32_32x32x16_bf16 v[0:15], v[194:197], v[76:79], v[0:15]
	v_add_u32_e32 v76, 0x1d800, v138
	ds_read_b128 v[194:197], v76
	v_add_u32_e32 v77, 0x1e400, v138
	v_add_u32_e32 v78, 0x1e800, v138
	v_add_u32_e32 v79, 0x1f000, v138
	s_waitcnt lgkmcnt(1)
	v_mfma_f32_32x32x16_bf16 v[0:15], v[198:201], v[72:75], v[0:15]
	v_add_u32_e32 v74, 0x1dc00, v138
	ds_read_b128 v[198:201], v74
	v_add_u32_e32 v75, 0x1e000, v138
	v_lshlrev_b64 v[72:73], 10, v[136:137]
	s_waitcnt lgkmcnt(1)
	v_mfma_f32_32x32x16_bf16 v[0:15], v[194:197], v[84:87], v[0:15]
	ds_read_b128 v[82:85], v75
	s_waitcnt lgkmcnt(1)
	v_mfma_f32_32x32x16_bf16 v[0:15], v[198:201], v[132:135], v[0:15]
	ds_read_b128 v[132:135], v77
	s_waitcnt lgkmcnt(1)
	v_mfma_f32_32x32x16_bf16 v[0:15], v[82:85], v[120:123], v[0:15]
	ds_read_b128 v[82:85], v78
	s_waitcnt lgkmcnt(1)
	v_mfma_f32_32x32x16_bf16 v[0:15], v[132:135], v[116:119], v[0:15]
	ds_read_b128 v[116:119], v81
	s_waitcnt lgkmcnt(1)
	v_mfma_f32_32x32x16_bf16 v[0:15], v[82:85], v[112:115], v[0:15]
	ds_read_b128 v[84:87], v79
	v_add_u32_e32 v83, 0x1f400, v138
	v_add_u32_e32 v82, 0x1f800, v138
	s_waitcnt lgkmcnt(1)
	v_mfma_f32_32x32x16_bf16 v[0:15], v[116:119], v[108:111], v[0:15]
	ds_read_b128 v[108:111], v83
	s_waitcnt lgkmcnt(1)
	v_mfma_f32_32x32x16_bf16 v[0:15], v[84:87], v[104:107], v[0:15]
	v_add_u32_e32 v84, 0x1fc00, v138
	s_waitcnt lgkmcnt(0)
	v_mfma_f32_32x32x16_bf16 v[0:15], v[108:111], v[100:103], v[0:15]
	ds_read_b128 v[98:101], v82
	ds_read_b128 v[102:105], v84
	s_waitcnt lgkmcnt(1)
; __device__ __forceinline__ unsigned cvt_pk_bf16(float lo, float hi) { unsigned r; asm volatile("v_cvt_pk_bf16_f32 %0, %1, %2" : "=v"(r) : "v"(lo), "v"(hi)); return r; }
; #define LAS __attribute__((address_space(3)))
; #define LAS __attribute__((address_space(3)))
; __device__ __forceinline__ void memattn_tile_lds(const Ctx& C, int pm, int h, unsigned char* lds) {
;     ...
;         float p[16];
; #pragma unroll
;         for (int r = 0; r < 16; ++r) { p[r] = __builtin_amdgcn_exp2f(S[r] * c); sum += p[r]; }
;         asm volatile("" : "+v"(sum));
; #pragma unroll
;         for (int s2 = 0; s2 < 2; ++s2)
; #pragma unroll
;             for (int j = 0; j < 4; ++j) pk[mb][s2][j] = cvt_pk_bf16(p[8 * s2 + 2 * j], p[8 * s2 + 2 * j + 1]);
;     }
;     sum += __shfl_xor(sum, 32); const float inv = 1.0f / sum;
;     __syncthreads();
; #pragma unroll 1
;     for (int i0 = 0; i0 < 16; i0 += 8) { u32x4 t[8];
; #pragma unroll
;       for (int i = 0; i < 8; ++i) t[i] = vG[(i0 + i) * 512 + tid];
; #pragma unroll
;       for (int i = 0; i < 8; ++i) *(LAS u32x4*)(ldsl + (size_t)((i0 + i) * 512 + tid) * 16) = t[i]; }
;     __syncthreads();
;     bf16_t* op = (bf16_t*)(C.ws + WS_OMEM) + (size_t)row * 1024 + h * 256 + 4 * hi;
; #pragma unroll
;     for (int db = 0; db < 8; ++db) {
;         f32x16 O = f32x16{};
; #pragma unroll
;         for (int mh = 0; mh < 2; ++mh) {
;             bf16x8 vf[8];
; #pragma unroll
;             for (int k8 = 0; k8 < 8; ++k8) vf[k8] = FRAG(db * 16 + mh * 8 + k8);
; #pragma unroll
;             for (int k8 = 0; k8 < 8; ++k8) { const int mb = mh * 4 + (k8 >> 1), s = k8 & 1;
;                 const u32x4 pw = (u32x4){pk[mb][s][0], pk[mb][s][1], pk[mb][s][2], pk[mb][s][3]};
;                 O = __builtin_amdgcn_mfma_f32_32x32x16_bf16(vf[k8], __builtin_bit_cast(bf16x8, pw), O, 0, 0, 0); }
	v_mfma_f32_32x32x16_bf16 v[0:15], v[98:101], v[68:71], v[0:15]
	v_mbcnt_lo_u32_b32 v68, -1, 0
	v_mbcnt_hi_u32_b32 v85, -1, v68
	s_waitcnt lgkmcnt(0)
	v_mfma_f32_32x32x16_bf16 v[0:15], v[102:105], v[64:67], v[0:15]
	s_nop 11
	v_mul_f32_e32 v0, v183, v0
	v_mul_f32_e32 v1, v183, v1
	v_exp_f32_e32 v0, v0
	v_mul_f32_e32 v2, v183, v2
	v_exp_f32_e32 v1, v1
	v_mul_f32_e32 v3, v183, v3
	v_exp_f32_e32 v2, v2
	v_mul_f32_e32 v4, v183, v4
	v_exp_f32_e32 v3, v3
	v_mul_f32_e32 v5, v183, v5
	v_exp_f32_e32 v4, v4
	v_add_f32_e32 v64, v193, v0
	v_mul_f32_e32 v6, v183, v6
	v_exp_f32_e32 v5, v5
	v_add_f32_e32 v64, v1, v64
	v_mul_f32_e32 v7, v183, v7
	v_exp_f32_e32 v6, v6
	v_add_f32_e32 v64, v2, v64
	v_mul_f32_e32 v8, v183, v8
	v_exp_f32_e32 v7, v7
	v_add_f32_e32 v64, v3, v64
	v_mul_f32_e32 v9, v183, v9
	v_exp_f32_e32 v8, v8
	v_add_f32_e32 v64, v4, v64
	v_mul_f32_e32 v10, v183, v10
	v_exp_f32_e32 v9, v9
	v_add_f32_e32 v64, v5, v64
	v_mul_f32_e32 v11, v183, v11
	v_exp_f32_e32 v10, v10
	v_add_f32_e32 v64, v6, v64
	v_mul_f32_e32 v12, v183, v12
	v_exp_f32_e32 v11, v11
	v_add_f32_e32 v64, v7, v64
	v_mul_f32_e32 v13, v183, v13
	v_exp_f32_e32 v12, v12
	v_add_f32_e32 v64, v8, v64
	v_mul_f32_e32 v14, v183, v14
	v_exp_f32_e32 v13, v13
	v_add_f32_e32 v64, v9, v64
	v_mul_f32_e32 v15, v183, v15
	v_exp_f32_e32 v14, v14
	v_add_f32_e32 v64, v10, v64
	v_exp_f32_e32 v15, v15
	v_add_f32_e32 v64, v11, v64
	v_add_f32_e32 v64, v12, v64
	v_add_f32_e32 v64, v13, v64
	v_add_f32_e32 v64, v14, v64
	v_add_f32_e32 v86, v15, v64
	v_cvt_pk_bf16_f32 v64, v0, v1
	v_cvt_pk_bf16_f32 v65, v2, v3
	v_cvt_pk_bf16_f32 v66, v4, v5
	v_cvt_pk_bf16_f32 v67, v6, v7
	v_cvt_pk_bf16_f32 v68, v8, v9
	v_cvt_pk_bf16_f32 v69, v10, v11
	v_cvt_pk_bf16_f32 v70, v12, v13
	v_cvt_pk_bf16_f32 v71, v14, v15
	s_barrier
.LBB0_3020:
	global_load_dwordx4 v[0:3], v[236:237], off
	v_lshl_add_u64 v[236:237], v[236:237], 0, v[238:239]
	global_load_dwordx4 v[4:7], v[236:237], off
	v_lshl_add_u64 v[236:237], v[236:237], 0, v[238:239]
	global_load_dwordx4 v[8:11], v[236:237], off
	v_lshl_add_u64 v[236:237], v[236:237], 0, v[238:239]
	global_load_dwordx4 v[12:15], v[236:237], off
	v_lshl_add_u64 v[236:237], v[236:237], 0, v[238:239]
	global_load_dwordx4 v[98:101], v[236:237], off
	v_lshl_add_u64 v[236:237], v[236:237], 0, v[238:239]
	global_load_dwordx4 v[102:105], v[236:237], off
	v_lshl_add_u64 v[236:237], v[236:237], 0, v[238:239]
	global_load_dwordx4 v[106:109], v[236:237], off
	v_lshl_add_u64 v[236:237], v[236:237], 0, v[238:239]
	global_load_dwordx4 v[110:113], v[236:237], off
	v_add_u32_e32 v87, 0x10000, v141
	s_waitcnt vmcnt(8)
	ds_write_b128 v141, v[204:207]
	ds_write_b128 v141, v[208:211] offset:8192
	ds_write_b128 v141, v[212:215] offset:16384
	ds_write_b128 v141, v[216:219] offset:24576
	ds_write_b128 v141, v[220:223] offset:32768
	ds_write_b128 v141, v[224:227] offset:40960
	ds_write_b128 v141, v[228:231] offset:49152
	ds_write_b128 v141, v[232:235] offset:57344
	s_waitcnt vmcnt(7)
	ds_write_b128 v87, v[0:3]
	s_waitcnt vmcnt(6)
	ds_write_b128 v87, v[4:7] offset:8192
	s_waitcnt vmcnt(5)
	ds_write_b128 v87, v[8:11] offset:16384
	s_waitcnt vmcnt(4)
	ds_write_b128 v87, v[12:15] offset:24576
	s_waitcnt vmcnt(3)
	ds_write_b128 v87, v[98:101] offset:32768
	s_waitcnt vmcnt(2)
	ds_write_b128 v87, v[102:105] offset:40960
	s_waitcnt vmcnt(1)
	ds_write_b128 v87, v[106:109] offset:49152
	s_waitcnt vmcnt(0)
	ds_write_b128 v87, v[110:113] offset:57344
	s_mov_b64 s[16:17], 0
	s_mov_b32 s18, 8
	s_waitcnt lgkmcnt(0)
	s_barrier
	ds_read_b128 v[0:3], v138
	ds_read_b128 v[98:101], v138 offset:1024
	s_waitcnt lgkmcnt(1)
	v_mfma_f32_32x32x16_bf16 v[0:15], v[0:3], v[16:19], 0
	v_and_b32_e32 v89, 64, v85
	v_xor_b32_e32 v87, 32, v85
	v_add_u32_e32 v89, 64, v89
	v_cmp_lt_i32_e32 vcc, v87, v89
	v_readlane_b32 s16, v250, 0
	v_readlane_b32 s20, v250, 4
	v_cndmask_b32_e32 v85, v85, v87, vcc
	s_waitcnt lgkmcnt(0)
	v_mfma_f32_32x32x16_bf16 v[0:15], v[98:101], v[20:23], v[0:15]
	ds_read_b128 v[98:101], v138 offset:2048
	ds_read_b128 v[102:105], v138 offset:3072
	v_lshlrev_b32_e32 v85, 2, v85
	ds_bpermute_b32 v85, v85, v86
	v_readlane_b32 s21, v250, 5
	v_lshlrev_b32_e32 v90, 2, v140
	v_ashrrev_i32_e32 v91, 31, v90
	v_lshl_add_u64 v[72:73], v[72:73], 1, s[20:21]
	s_waitcnt lgkmcnt(2)
	v_mfma_f32_32x32x16_bf16 v[0:15], v[98:101], v[24:27], v[0:15]
	v_lshl_add_u64 v[72:73], s[14:15], 1, v[72:73]
	s_mov_b64 s[0:1], 0x16100000
	v_lshl_add_u64 v[90:91], v[90:91], 1, v[72:73]
	s_waitcnt lgkmcnt(0)
	v_add_f32_e32 v85, v86, v85
	v_lshl_add_u64 v[72:73], v[90:91], 0, s[0:1]
	v_div_scale_f32 v89, s[0:1], v85, v85, 1.0
	v_mfma_f32_32x32x16_bf16 v[0:15], v[102:105], v[28:31], v[0:15]
	ds_read_b128 v[98:101], v138 offset:4096
	ds_read_b128 v[102:105], v138 offset:5120
	v_rcp_f32_e32 v93, v89
	s_mov_b32 s16, 0x16100000
	v_add_co_u32_e32 v86, vcc, s16, v90
	v_readlane_b32 s17, v250, 1
	s_nop 0
	v_addc_co_u32_e32 v87, vcc, 0, v91, vcc
	s_waitcnt lgkmcnt(1)
	v_mfma_f32_32x32x16_bf16 v[0:15], v[98:101], v[32:35], v[0:15]
	v_fma_f32 v91, -v89, v93, 1.0
	v_div_scale_f32 v90, vcc, 1.0, v85, 1.0
	v_fmac_f32_e32 v93, v91, v93
	v_mul_f32_e32 v91, v90, v93
	v_fma_f32 v94, -v89, v91, v90
	v_fmac_f32_e32 v91, v94, v93
	s_waitcnt lgkmcnt(0)
	v_mfma_f32_32x32x16_bf16 v[0:15], v[102:105], v[36:39], v[0:15]
	ds_read_b128 v[98:101], v138 offset:6144
	ds_read_b128 v[102:105], v138 offset:7168
	v_fma_f32 v89, -v89, v91, v90
	v_div_fmas_f32 v89, v89, v93, v91
	v_div_fixup_f32 v85, v89, v85, 1.0
	v_readlane_b32 s18, v250, 2
	v_readlane_b32 s19, v250, 3
	v_readlane_b32 s22, v250, 6
	s_waitcnt lgkmcnt(1)
	v_mfma_f32_32x32x16_bf16 v[0:15], v[98:101], v[40:43], v[0:15]
	v_readlane_b32 s23, v250, 7
	s_waitcnt lgkmcnt(0)
; __device__ __forceinline__ unsigned cvt_pk_bf16(float lo, float hi) { unsigned r; asm volatile("v_cvt_pk_bf16_f32 %0, %1, %2" : "=v"(r) : "v"(lo), "v"(hi)); return r; }
; __device__ __forceinline__ void memattn_tile_lds(const Ctx& C, int pm, int h, unsigned char* lds) {
;     ...
;     for (int db = 0; db < 8; ++db) {
;         f32x16 O = f32x16{};
; #pragma unroll
;         for (int mh = 0; mh < 2; ++mh) {
;             bf16x8 vf[8];
; #pragma unroll
;             for (int k8 = 0; k8 < 8; ++k8) vf[k8] = FRAG(db * 16 + mh * 8 + k8);
; #pragma unroll
;             for (int k8 = 0; k8 < 8; ++k8) { const int mb = mh * 4 + (k8 >> 1), s = k8 & 1;
;                 const u32x4 pw = (u32x4){pk[mb][s][0], pk[mb][s][1], pk[mb][s][2], pk[mb][s][3]};
;                 O = __builtin_amdgcn_mfma_f32_32x32x16_bf16(vf[k8], __builtin_bit_cast(bf16x8, pw), O, 0, 0, 0); }
;         }
; #pragma unroll
;         for (int rq = 0; rq < 4; ++rq) {
;             const unsigned w0 = cvt_pk_bf16(O[4 * rq] * inv, O[4 * rq + 1] * inv), w1 = cvt_pk_bf16(O[4 * rq + 2] * inv, O[4 * rq + 3] * inv);
;             *(u64*)(op + 32 * db + 8 * rq) = (u64)w0 | ((u64)w1 << 32);
;         }
;     }
	v_mfma_f32_32x32x16_bf16 v[0:15], v[102:105], v[44:47], v[0:15]
	ds_read_b128 v[98:101], v138 offset:8192
	ds_read_b128 v[102:105], v138 offset:9216
	s_waitcnt lgkmcnt(1)
	v_mfma_f32_32x32x16_bf16 v[0:15], v[98:101], v[48:51], v[0:15]
	ds_read_b128 v[98:101], v138 offset:10240
	s_waitcnt lgkmcnt(1)
	v_mfma_f32_32x32x16_bf16 v[0:15], v[102:105], v[52:55], v[0:15]
	ds_read_b128 v[102:105], v138 offset:11264
	s_waitcnt lgkmcnt(1)
	v_mfma_f32_32x32x16_bf16 v[0:15], v[98:101], v[56:59], v[0:15]
	ds_read_b128 v[98:101], v138 offset:12288
	ds_read_b128 v[106:109], v138 offset:13312
	ds_read_b128 v[110:113], v138 offset:14336
	ds_read_b128 v[114:117], v138 offset:15360
	s_waitcnt lgkmcnt(4)
	v_mfma_f32_32x32x16_bf16 v[0:15], v[102:105], v[60:63], v[0:15]
	s_waitcnt lgkmcnt(3)
	v_mfma_f32_32x32x16_bf16 v[0:15], v[98:101], v[124:127], v[0:15]
	s_waitcnt lgkmcnt(2)
	v_mfma_f32_32x32x16_bf16 v[0:15], v[106:109], v[128:131], v[0:15]
	s_waitcnt lgkmcnt(1)
	v_mfma_f32_32x32x16_bf16 v[0:15], v[110:113], v[64:67], v[0:15]
	s_waitcnt lgkmcnt(0)
	v_mfma_f32_32x32x16_bf16 v[0:15], v[114:117], v[68:71], v[0:15]
	s_nop 11
	v_mul_f32_e32 v0, v85, v0
	v_mul_f32_e32 v1, v85, v1
	v_mul_f32_e32 v2, v85, v2
	v_mul_f32_e32 v3, v85, v3
	v_cvt_pk_bf16_f32 v0, v0, v1
	v_cvt_pk_bf16_f32 v1, v2, v3
	v_mul_f32_e32 v4, v85, v4
	v_mul_f32_e32 v5, v85, v5
	v_mul_f32_e32 v6, v85, v6
	v_mul_f32_e32 v7, v85, v7
	global_store_dwordx2 v[86:87], v[0:1], off
	v_cvt_pk_bf16_f32 v0, v4, v5
	v_cvt_pk_bf16_f32 v1, v6, v7
	v_mul_f32_e32 v8, v85, v8
	v_mul_f32_e32 v9, v85, v9
	v_mul_f32_e32 v10, v85, v10
	v_mul_f32_e32 v11, v85, v11
	global_store_dwordx2 v[72:73], v[0:1], off offset:16
	v_cvt_pk_bf16_f32 v0, v8, v9
	v_cvt_pk_bf16_f32 v1, v10, v11
	v_mul_f32_e32 v12, v85, v12
	v_mul_f32_e32 v13, v85, v13
	v_mul_f32_e32 v14, v85, v14
	v_mul_f32_e32 v15, v85, v15
	global_store_dwordx2 v[72:73], v[0:1], off offset:32
	v_cvt_pk_bf16_f32 v86, v12, v13
	v_cvt_pk_bf16_f32 v87, v14, v15
	ds_read_b128 v[0:3], v138 offset:16384
	ds_read_b128 v[98:101], v138 offset:17408
	s_waitcnt lgkmcnt(1)
	v_mfma_f32_32x32x16_bf16 v[0:15], v[0:3], v[16:19], 0
	s_waitcnt lgkmcnt(0)
	v_mfma_f32_32x32x16_bf16 v[0:15], v[98:101], v[20:23], v[0:15]
	ds_read_b128 v[98:101], v138 offset:18432
	ds_read_b128 v[102:105], v138 offset:19456
	s_waitcnt lgkmcnt(1)
	v_mfma_f32_32x32x16_bf16 v[0:15], v[98:101], v[24:27], v[0:15]
	s_waitcnt lgkmcnt(0)
	v_mfma_f32_32x32x16_bf16 v[0:15], v[102:105], v[28:31], v[0:15]
	ds_read_b128 v[98:101], v138 offset:20480
	ds_read_b128 v[102:105], v138 offset:21504
	s_waitcnt lgkmcnt(1)
	v_mfma_f32_32x32x16_bf16 v[0:15], v[98:101], v[32:35], v[0:15]
	s_waitcnt lgkmcnt(0)
	v_mfma_f32_32x32x16_bf16 v[0:15], v[102:105], v[36:39], v[0:15]
	ds_read_b128 v[98:101], v138 offset:22528
	ds_read_b128 v[102:105], v138 offset:23552
	s_waitcnt lgkmcnt(1)
	v_mfma_f32_32x32x16_bf16 v[0:15], v[98:101], v[40:43], v[0:15]
	s_waitcnt lgkmcnt(0)
	v_mfma_f32_32x32x16_bf16 v[0:15], v[102:105], v[44:47], v[0:15]
	ds_read_b128 v[98:101], v138 offset:24576
	ds_read_b128 v[102:105], v138 offset:25600
	s_waitcnt lgkmcnt(1)
	v_mfma_f32_32x32x16_bf16 v[0:15], v[98:101], v[48:51], v[0:15]
	s_waitcnt lgkmcnt(0)
	v_mfma_f32_32x32x16_bf16 v[0:15], v[102:105], v[52:55], v[0:15]
	ds_read_b128 v[98:101], v138 offset:26624
	ds_read_b128 v[102:105], v138 offset:27648
	s_waitcnt lgkmcnt(1)
	v_mfma_f32_32x32x16_bf16 v[0:15], v[98:101], v[56:59], v[0:15]
	s_waitcnt lgkmcnt(0)
	v_mfma_f32_32x32x16_bf16 v[0:15], v[102:105], v[60:63], v[0:15]
	ds_read_b128 v[98:101], v138 offset:28672
	ds_read_b128 v[102:105], v138 offset:29696
	s_waitcnt lgkmcnt(1)
	v_mfma_f32_32x32x16_bf16 v[0:15], v[98:101], v[124:127], v[0:15]
	s_waitcnt lgkmcnt(0)
	v_mfma_f32_32x32x16_bf16 v[0:15], v[102:105], v[128:131], v[0:15]
	ds_read_b128 v[98:101], v138 offset:30720
	ds_read_b128 v[102:105], v138 offset:31744
	global_store_dwordx2 v[72:73], v[86:87], off offset:48
	s_waitcnt lgkmcnt(1)
	v_mfma_f32_32x32x16_bf16 v[0:15], v[98:101], v[64:67], v[0:15]
	s_waitcnt lgkmcnt(0)
	v_mfma_f32_32x32x16_bf16 v[0:15], v[102:105], v[68:71], v[0:15]
	s_nop 11
	v_mul_f32_e32 v0, v85, v0
	v_mul_f32_e32 v1, v85, v1
	v_mul_f32_e32 v2, v85, v2
	v_mul_f32_e32 v3, v85, v3
	v_cvt_pk_bf16_f32 v0, v0, v1
	v_cvt_pk_bf16_f32 v1, v2, v3
	v_mul_f32_e32 v4, v85, v4
	v_mul_f32_e32 v5, v85, v5
	v_mul_f32_e32 v6, v85, v6
	v_mul_f32_e32 v7, v85, v7
	global_store_dwordx2 v[72:73], v[0:1], off offset:64
	v_cvt_pk_bf16_f32 v0, v4, v5
	v_cvt_pk_bf16_f32 v1, v6, v7
	v_mul_f32_e32 v8, v85, v8
	v_mul_f32_e32 v9, v85, v9
	v_mul_f32_e32 v10, v85, v10
	v_mul_f32_e32 v11, v85, v11
	global_store_dwordx2 v[72:73], v[0:1], off offset:80
	v_cvt_pk_bf16_f32 v0, v8, v9
	v_cvt_pk_bf16_f32 v1, v10, v11
	v_mul_f32_e32 v12, v85, v12
	v_mul_f32_e32 v13, v85, v13
	v_mul_f32_e32 v14, v85, v14
	v_mul_f32_e32 v15, v85, v15
	global_store_dwordx2 v[72:73], v[0:1], off offset:96
	v_cvt_pk_bf16_f32 v86, v12, v13
	v_cvt_pk_bf16_f32 v87, v14, v15
	ds_read_b128 v[0:3], v138 offset:32768
	ds_read_b128 v[98:101], v138 offset:33792
	s_waitcnt lgkmcnt(1)
	v_mfma_f32_32x32x16_bf16 v[0:15], v[0:3], v[16:19], 0
	s_waitcnt lgkmcnt(0)
	v_mfma_f32_32x32x16_bf16 v[0:15], v[98:101], v[20:23], v[0:15]
	ds_read_b128 v[98:101], v138 offset:34816
	ds_read_b128 v[102:105], v138 offset:35840
	s_waitcnt lgkmcnt(1)
	v_mfma_f32_32x32x16_bf16 v[0:15], v[98:101], v[24:27], v[0:15]
	s_waitcnt lgkmcnt(0)
	v_mfma_f32_32x32x16_bf16 v[0:15], v[102:105], v[28:31], v[0:15]
	ds_read_b128 v[98:101], v138 offset:36864
	ds_read_b128 v[102:105], v138 offset:37888
	s_waitcnt lgkmcnt(1)
	v_mfma_f32_32x32x16_bf16 v[0:15], v[98:101], v[32:35], v[0:15]
	s_waitcnt lgkmcnt(0)
; __device__ __forceinline__ unsigned cvt_pk_bf16(float lo, float hi) { unsigned r; asm volatile("v_cvt_pk_bf16_f32 %0, %1, %2" : "=v"(r) : "v"(lo), "v"(hi)); return r; }
; __device__ __forceinline__ void memattn_tile_lds(const Ctx& C, int pm, int h, unsigned char* lds) {
;     ...
;     for (int db = 0; db < 8; ++db) {
;         f32x16 O = f32x16{};
; #pragma unroll
;         for (int mh = 0; mh < 2; ++mh) {
;             bf16x8 vf[8];
; #pragma unroll
;             for (int k8 = 0; k8 < 8; ++k8) vf[k8] = FRAG(db * 16 + mh * 8 + k8);
; #pragma unroll
;             for (int k8 = 0; k8 < 8; ++k8) { const int mb = mh * 4 + (k8 >> 1), s = k8 & 1;
;                 const u32x4 pw = (u32x4){pk[mb][s][0], pk[mb][s][1], pk[mb][s][2], pk[mb][s][3]};
;                 O = __builtin_amdgcn_mfma_f32_32x32x16_bf16(vf[k8], __builtin_bit_cast(bf16x8, pw), O, 0, 0, 0); }
;         }
; #pragma unroll
;         for (int rq = 0; rq < 4; ++rq) {
;             const unsigned w0 = cvt_pk_bf16(O[4 * rq] * inv, O[4 * rq + 1] * inv), w1 = cvt_pk_bf16(O[4 * rq + 2] * inv, O[4 * rq + 3] * inv);
;             *(u64*)(op + 32 * db + 8 * rq) = (u64)w0 | ((u64)w1 << 32);
;         }
;     }
	v_mfma_f32_32x32x16_bf16 v[0:15], v[102:105], v[36:39], v[0:15]
	ds_read_b128 v[98:101], v138 offset:38912
	ds_read_b128 v[102:105], v138 offset:39936
	s_waitcnt lgkmcnt(1)
	v_mfma_f32_32x32x16_bf16 v[0:15], v[98:101], v[40:43], v[0:15]
	s_waitcnt lgkmcnt(0)
	v_mfma_f32_32x32x16_bf16 v[0:15], v[102:105], v[44:47], v[0:15]
	ds_read_b128 v[98:101], v138 offset:40960
	ds_read_b128 v[102:105], v138 offset:41984
	s_waitcnt lgkmcnt(1)
	v_mfma_f32_32x32x16_bf16 v[0:15], v[98:101], v[48:51], v[0:15]
	s_waitcnt lgkmcnt(0)
	v_mfma_f32_32x32x16_bf16 v[0:15], v[102:105], v[52:55], v[0:15]
	ds_read_b128 v[98:101], v138 offset:43008
	ds_read_b128 v[102:105], v138 offset:44032
	s_waitcnt lgkmcnt(1)
	v_mfma_f32_32x32x16_bf16 v[0:15], v[98:101], v[56:59], v[0:15]
	s_waitcnt lgkmcnt(0)
	v_mfma_f32_32x32x16_bf16 v[0:15], v[102:105], v[60:63], v[0:15]
	ds_read_b128 v[98:101], v138 offset:45056
	ds_read_b128 v[102:105], v138 offset:46080
	s_waitcnt lgkmcnt(1)
	v_mfma_f32_32x32x16_bf16 v[0:15], v[98:101], v[124:127], v[0:15]
	s_waitcnt lgkmcnt(0)
	v_mfma_f32_32x32x16_bf16 v[0:15], v[102:105], v[128:131], v[0:15]
	ds_read_b128 v[98:101], v138 offset:47104
	ds_read_b128 v[102:105], v138 offset:48128
	global_store_dwordx2 v[72:73], v[86:87], off offset:112
	s_waitcnt lgkmcnt(1)
	v_mfma_f32_32x32x16_bf16 v[0:15], v[98:101], v[64:67], v[0:15]
	s_waitcnt lgkmcnt(0)
	v_mfma_f32_32x32x16_bf16 v[0:15], v[102:105], v[68:71], v[0:15]
	s_nop 11
	v_mul_f32_e32 v0, v85, v0
	v_mul_f32_e32 v1, v85, v1
	v_mul_f32_e32 v2, v85, v2
	v_mul_f32_e32 v3, v85, v3
	v_cvt_pk_bf16_f32 v0, v0, v1
	v_cvt_pk_bf16_f32 v1, v2, v3
	v_mul_f32_e32 v4, v85, v4
	v_mul_f32_e32 v5, v85, v5
	v_mul_f32_e32 v6, v85, v6
	v_mul_f32_e32 v7, v85, v7
	global_store_dwordx2 v[72:73], v[0:1], off offset:128
	v_cvt_pk_bf16_f32 v0, v4, v5
	v_cvt_pk_bf16_f32 v1, v6, v7
	v_mul_f32_e32 v8, v85, v8
	v_mul_f32_e32 v9, v85, v9
	v_mul_f32_e32 v10, v85, v10
	v_mul_f32_e32 v11, v85, v11
	global_store_dwordx2 v[72:73], v[0:1], off offset:144
	v_cvt_pk_bf16_f32 v0, v8, v9
	v_cvt_pk_bf16_f32 v1, v10, v11
	v_mul_f32_e32 v12, v85, v12
	v_mul_f32_e32 v13, v85, v13
	v_mul_f32_e32 v14, v85, v14
	v_mul_f32_e32 v15, v85, v15
	global_store_dwordx2 v[72:73], v[0:1], off offset:160
	v_cvt_pk_bf16_f32 v86, v12, v13
	v_cvt_pk_bf16_f32 v87, v14, v15
	ds_read_b128 v[0:3], v138 offset:49152
	ds_read_b128 v[98:101], v138 offset:50176
	s_waitcnt lgkmcnt(1)
	v_mfma_f32_32x32x16_bf16 v[0:15], v[0:3], v[16:19], 0
	s_waitcnt lgkmcnt(0)
	v_mfma_f32_32x32x16_bf16 v[0:15], v[98:101], v[20:23], v[0:15]
	ds_read_b128 v[98:101], v138 offset:51200
	ds_read_b128 v[102:105], v138 offset:52224
	s_waitcnt lgkmcnt(1)
	v_mfma_f32_32x32x16_bf16 v[0:15], v[98:101], v[24:27], v[0:15]
	s_waitcnt lgkmcnt(0)
	v_mfma_f32_32x32x16_bf16 v[0:15], v[102:105], v[28:31], v[0:15]
	ds_read_b128 v[98:101], v138 offset:53248
	ds_read_b128 v[102:105], v138 offset:54272
	s_waitcnt lgkmcnt(1)
	v_mfma_f32_32x32x16_bf16 v[0:15], v[98:101], v[32:35], v[0:15]
	s_waitcnt lgkmcnt(0)
	v_mfma_f32_32x32x16_bf16 v[0:15], v[102:105], v[36:39], v[0:15]
	ds_read_b128 v[98:101], v138 offset:55296
	ds_read_b128 v[102:105], v138 offset:56320
	s_waitcnt lgkmcnt(1)
	v_mfma_f32_32x32x16_bf16 v[0:15], v[98:101], v[40:43], v[0:15]
	s_waitcnt lgkmcnt(0)
	v_mfma_f32_32x32x16_bf16 v[0:15], v[102:105], v[44:47], v[0:15]
	ds_read_b128 v[98:101], v138 offset:57344
	ds_read_b128 v[102:105], v138 offset:58368
	s_waitcnt lgkmcnt(1)
	v_mfma_f32_32x32x16_bf16 v[0:15], v[98:101], v[48:51], v[0:15]
	s_waitcnt lgkmcnt(0)
	v_mfma_f32_32x32x16_bf16 v[0:15], v[102:105], v[52:55], v[0:15]
	ds_read_b128 v[98:101], v138 offset:59392
	ds_read_b128 v[102:105], v138 offset:60416
	s_waitcnt lgkmcnt(1)
	v_mfma_f32_32x32x16_bf16 v[0:15], v[98:101], v[56:59], v[0:15]
	s_waitcnt lgkmcnt(0)
	v_mfma_f32_32x32x16_bf16 v[0:15], v[102:105], v[60:63], v[0:15]
	ds_read_b128 v[98:101], v138 offset:61440
	ds_read_b128 v[102:105], v138 offset:62464
	s_waitcnt lgkmcnt(1)
	v_mfma_f32_32x32x16_bf16 v[0:15], v[98:101], v[124:127], v[0:15]
	s_waitcnt lgkmcnt(0)
	v_mfma_f32_32x32x16_bf16 v[0:15], v[102:105], v[128:131], v[0:15]
	ds_read_b128 v[98:101], v138 offset:63488
	ds_read_b128 v[102:105], v138 offset:64512
	global_store_dwordx2 v[72:73], v[86:87], off offset:176
	s_waitcnt lgkmcnt(1)
	v_mfma_f32_32x32x16_bf16 v[0:15], v[98:101], v[64:67], v[0:15]
	s_waitcnt lgkmcnt(0)
	v_mfma_f32_32x32x16_bf16 v[0:15], v[102:105], v[68:71], v[0:15]
	s_nop 11
	v_mul_f32_e32 v0, v85, v0
	v_mul_f32_e32 v1, v85, v1
	v_mul_f32_e32 v2, v85, v2
	v_mul_f32_e32 v3, v85, v3
	v_cvt_pk_bf16_f32 v0, v0, v1
	v_cvt_pk_bf16_f32 v1, v2, v3
	v_mul_f32_e32 v4, v85, v4
	v_mul_f32_e32 v5, v85, v5
	v_mul_f32_e32 v6, v85, v6
	v_mul_f32_e32 v7, v85, v7
	global_store_dwordx2 v[72:73], v[0:1], off offset:192
	v_cvt_pk_bf16_f32 v0, v4, v5
	v_cvt_pk_bf16_f32 v1, v6, v7
	v_mul_f32_e32 v8, v85, v8
	v_mul_f32_e32 v9, v85, v9
	v_mul_f32_e32 v10, v85, v10
	v_mul_f32_e32 v11, v85, v11
	global_store_dwordx2 v[72:73], v[0:1], off offset:208
	v_cvt_pk_bf16_f32 v0, v8, v9
	v_cvt_pk_bf16_f32 v1, v10, v11
	v_mul_f32_e32 v12, v85, v12
	v_mul_f32_e32 v13, v85, v13
	v_mul_f32_e32 v14, v85, v14
	v_mul_f32_e32 v15, v85, v15
	global_store_dwordx2 v[72:73], v[0:1], off offset:224
	v_cvt_pk_bf16_f32 v86, v12, v13
	v_cvt_pk_bf16_f32 v87, v14, v15
	ds_read_b128 v[0:3], v142
	ds_read_b128 v[98:101], v143
	s_waitcnt lgkmcnt(1)
	v_mfma_f32_32x32x16_bf16 v[0:15], v[0:3], v[16:19], 0
	s_waitcnt lgkmcnt(0)
	v_mfma_f32_32x32x16_bf16 v[0:15], v[98:101], v[20:23], v[0:15]
	ds_read_b128 v[98:101], v144
	ds_read_b128 v[102:105], v146
	s_waitcnt lgkmcnt(1)
	v_mfma_f32_32x32x16_bf16 v[0:15], v[98:101], v[24:27], v[0:15]
	s_waitcnt lgkmcnt(0)
; __device__ __forceinline__ unsigned cvt_pk_bf16(float lo, float hi) { unsigned r; asm volatile("v_cvt_pk_bf16_f32 %0, %1, %2" : "=v"(r) : "v"(lo), "v"(hi)); return r; }
; __device__ __forceinline__ void memattn_tile_lds(const Ctx& C, int pm, int h, unsigned char* lds) {
;     ...
;     for (int db = 0; db < 8; ++db) {
;         f32x16 O = f32x16{};
; #pragma unroll
;         for (int mh = 0; mh < 2; ++mh) {
;             bf16x8 vf[8];
; #pragma unroll
;             for (int k8 = 0; k8 < 8; ++k8) vf[k8] = FRAG(db * 16 + mh * 8 + k8);
; #pragma unroll
;             for (int k8 = 0; k8 < 8; ++k8) { const int mb = mh * 4 + (k8 >> 1), s = k8 & 1;
;                 const u32x4 pw = (u32x4){pk[mb][s][0], pk[mb][s][1], pk[mb][s][2], pk[mb][s][3]};
;                 O = __builtin_amdgcn_mfma_f32_32x32x16_bf16(vf[k8], __builtin_bit_cast(bf16x8, pw), O, 0, 0, 0); }
;         }
; #pragma unroll
;         for (int rq = 0; rq < 4; ++rq) {
;             const unsigned w0 = cvt_pk_bf16(O[4 * rq] * inv, O[4 * rq + 1] * inv), w1 = cvt_pk_bf16(O[4 * rq + 2] * inv, O[4 * rq + 3] * inv);
;             *(u64*)(op + 32 * db + 8 * rq) = (u64)w0 | ((u64)w1 << 32);
;         }
;     }
	v_mfma_f32_32x32x16_bf16 v[0:15], v[102:105], v[28:31], v[0:15]
	ds_read_b128 v[98:101], v145
	ds_read_b128 v[102:105], v148
	s_waitcnt lgkmcnt(1)
	v_mfma_f32_32x32x16_bf16 v[0:15], v[98:101], v[32:35], v[0:15]
	s_waitcnt lgkmcnt(0)
	v_mfma_f32_32x32x16_bf16 v[0:15], v[102:105], v[36:39], v[0:15]
	ds_read_b128 v[98:101], v147
	ds_read_b128 v[102:105], v149
	s_waitcnt lgkmcnt(1)
	v_mfma_f32_32x32x16_bf16 v[0:15], v[98:101], v[40:43], v[0:15]
	s_waitcnt lgkmcnt(0)
	v_mfma_f32_32x32x16_bf16 v[0:15], v[102:105], v[44:47], v[0:15]
	ds_read_b128 v[98:101], v150
	ds_read_b128 v[102:105], v151
	s_waitcnt lgkmcnt(1)
	v_mfma_f32_32x32x16_bf16 v[0:15], v[98:101], v[48:51], v[0:15]
	s_waitcnt lgkmcnt(0)
	v_mfma_f32_32x32x16_bf16 v[0:15], v[102:105], v[52:55], v[0:15]
	ds_read_b128 v[98:101], v152
	ds_read_b128 v[102:105], v154
	s_waitcnt lgkmcnt(1)
	v_mfma_f32_32x32x16_bf16 v[0:15], v[98:101], v[56:59], v[0:15]
	s_waitcnt lgkmcnt(0)
	v_mfma_f32_32x32x16_bf16 v[0:15], v[102:105], v[60:63], v[0:15]
	ds_read_b128 v[98:101], v153
	ds_read_b128 v[102:105], v156
	s_waitcnt lgkmcnt(1)
	v_mfma_f32_32x32x16_bf16 v[0:15], v[98:101], v[124:127], v[0:15]
	s_waitcnt lgkmcnt(0)
	v_mfma_f32_32x32x16_bf16 v[0:15], v[102:105], v[128:131], v[0:15]
	ds_read_b128 v[98:101], v155
	ds_read_b128 v[102:105], v157
	global_store_dwordx2 v[72:73], v[86:87], off offset:240
	s_waitcnt lgkmcnt(1)
	v_mfma_f32_32x32x16_bf16 v[0:15], v[98:101], v[64:67], v[0:15]
	s_waitcnt lgkmcnt(0)
	v_mfma_f32_32x32x16_bf16 v[0:15], v[102:105], v[68:71], v[0:15]
	s_nop 11
	v_mul_f32_e32 v0, v85, v0
	v_mul_f32_e32 v1, v85, v1
	v_mul_f32_e32 v2, v85, v2
	v_mul_f32_e32 v3, v85, v3
	v_cvt_pk_bf16_f32 v0, v0, v1
	v_cvt_pk_bf16_f32 v1, v2, v3
	v_mul_f32_e32 v4, v85, v4
	v_mul_f32_e32 v5, v85, v5
	v_mul_f32_e32 v6, v85, v6
	v_mul_f32_e32 v7, v85, v7
	global_store_dwordx2 v[72:73], v[0:1], off offset:256
	v_cvt_pk_bf16_f32 v0, v4, v5
	v_cvt_pk_bf16_f32 v1, v6, v7
	v_mul_f32_e32 v8, v85, v8
	v_mul_f32_e32 v9, v85, v9
	v_mul_f32_e32 v10, v85, v10
	v_mul_f32_e32 v11, v85, v11
	global_store_dwordx2 v[72:73], v[0:1], off offset:272
	v_cvt_pk_bf16_f32 v0, v8, v9
	v_cvt_pk_bf16_f32 v1, v10, v11
	v_mul_f32_e32 v12, v85, v12
	v_mul_f32_e32 v13, v85, v13
	v_mul_f32_e32 v14, v85, v14
	v_mul_f32_e32 v15, v85, v15
	global_store_dwordx2 v[72:73], v[0:1], off offset:288
	v_cvt_pk_bf16_f32 v86, v12, v13
	v_cvt_pk_bf16_f32 v87, v14, v15
	ds_read_b128 v[0:3], v158
	ds_read_b128 v[98:101], v159
	s_waitcnt lgkmcnt(1)
	v_mfma_f32_32x32x16_bf16 v[0:15], v[0:3], v[16:19], 0
	s_waitcnt lgkmcnt(0)
	v_mfma_f32_32x32x16_bf16 v[0:15], v[98:101], v[20:23], v[0:15]
	ds_read_b128 v[98:101], v160
	ds_read_b128 v[102:105], v162
	s_waitcnt lgkmcnt(1)
	v_mfma_f32_32x32x16_bf16 v[0:15], v[98:101], v[24:27], v[0:15]
	s_waitcnt lgkmcnt(0)
	v_mfma_f32_32x32x16_bf16 v[0:15], v[102:105], v[28:31], v[0:15]
	ds_read_b128 v[98:101], v161
	ds_read_b128 v[102:105], v164
	s_waitcnt lgkmcnt(1)
	v_mfma_f32_32x32x16_bf16 v[0:15], v[98:101], v[32:35], v[0:15]
	s_waitcnt lgkmcnt(0)
	v_mfma_f32_32x32x16_bf16 v[0:15], v[102:105], v[36:39], v[0:15]
	ds_read_b128 v[98:101], v163
	ds_read_b128 v[102:105], v165
	s_waitcnt lgkmcnt(1)
	v_mfma_f32_32x32x16_bf16 v[0:15], v[98:101], v[40:43], v[0:15]
	s_waitcnt lgkmcnt(0)
	v_mfma_f32_32x32x16_bf16 v[0:15], v[102:105], v[44:47], v[0:15]
	ds_read_b128 v[98:101], v166
	ds_read_b128 v[102:105], v167
	s_waitcnt lgkmcnt(1)
	v_mfma_f32_32x32x16_bf16 v[0:15], v[98:101], v[48:51], v[0:15]
	s_waitcnt lgkmcnt(0)
	v_mfma_f32_32x32x16_bf16 v[0:15], v[102:105], v[52:55], v[0:15]
	ds_read_b128 v[98:101], v168
	ds_read_b128 v[102:105], v170
	s_waitcnt lgkmcnt(1)
	v_mfma_f32_32x32x16_bf16 v[0:15], v[98:101], v[56:59], v[0:15]
	s_waitcnt lgkmcnt(0)
	v_mfma_f32_32x32x16_bf16 v[0:15], v[102:105], v[60:63], v[0:15]
	ds_read_b128 v[98:101], v169
	ds_read_b128 v[102:105], v172
	s_waitcnt lgkmcnt(1)
	v_mfma_f32_32x32x16_bf16 v[0:15], v[98:101], v[124:127], v[0:15]
	s_waitcnt lgkmcnt(0)
	v_mfma_f32_32x32x16_bf16 v[0:15], v[102:105], v[128:131], v[0:15]
	ds_read_b128 v[98:101], v171
	ds_read_b128 v[102:105], v173
	global_store_dwordx2 v[72:73], v[86:87], off offset:304
	s_waitcnt lgkmcnt(1)
	v_mfma_f32_32x32x16_bf16 v[0:15], v[98:101], v[64:67], v[0:15]
	s_waitcnt lgkmcnt(0)
	v_mfma_f32_32x32x16_bf16 v[0:15], v[102:105], v[68:71], v[0:15]
	s_nop 11
	v_mul_f32_e32 v0, v85, v0
	v_mul_f32_e32 v1, v85, v1
	v_mul_f32_e32 v2, v85, v2
	v_mul_f32_e32 v3, v85, v3
	v_cvt_pk_bf16_f32 v0, v0, v1
	v_cvt_pk_bf16_f32 v1, v2, v3
	v_mul_f32_e32 v4, v85, v4
	v_mul_f32_e32 v5, v85, v5
	v_mul_f32_e32 v6, v85, v6
	v_mul_f32_e32 v7, v85, v7
	global_store_dwordx2 v[72:73], v[0:1], off offset:320
	v_cvt_pk_bf16_f32 v0, v4, v5
	v_cvt_pk_bf16_f32 v1, v6, v7
	v_mul_f32_e32 v8, v85, v8
	v_mul_f32_e32 v9, v85, v9
	v_mul_f32_e32 v10, v85, v10
	v_mul_f32_e32 v11, v85, v11
	global_store_dwordx2 v[72:73], v[0:1], off offset:336
	v_cvt_pk_bf16_f32 v0, v8, v9
	v_cvt_pk_bf16_f32 v1, v10, v11
	v_mul_f32_e32 v12, v85, v12
	v_mul_f32_e32 v13, v85, v13
	v_mul_f32_e32 v14, v85, v14
	v_mul_f32_e32 v15, v85, v15
	global_store_dwordx2 v[72:73], v[0:1], off offset:352
	v_cvt_pk_bf16_f32 v86, v12, v13
	v_cvt_pk_bf16_f32 v87, v14, v15
	ds_read_b128 v[0:3], v174
	ds_read_b128 v[98:101], v175
	s_waitcnt lgkmcnt(1)
	v_mfma_f32_32x32x16_bf16 v[0:15], v[0:3], v[16:19], 0
	s_waitcnt lgkmcnt(0)
; __device__ __forceinline__ unsigned cvt_pk_bf16(float lo, float hi) { unsigned r; asm volatile("v_cvt_pk_bf16_f32 %0, %1, %2" : "=v"(r) : "v"(lo), "v"(hi)); return r; }
; __device__ __forceinline__ void memattn_tile_lds(const Ctx& C, int pm, int h, unsigned char* lds) {
;     ...
;     for (int db = 0; db < 8; ++db) {
;         f32x16 O = f32x16{};
; #pragma unroll
;         for (int mh = 0; mh < 2; ++mh) {
;             bf16x8 vf[8];
; #pragma unroll
;             for (int k8 = 0; k8 < 8; ++k8) vf[k8] = FRAG(db * 16 + mh * 8 + k8);
; #pragma unroll
;             for (int k8 = 0; k8 < 8; ++k8) { const int mb = mh * 4 + (k8 >> 1), s = k8 & 1;
;                 const u32x4 pw = (u32x4){pk[mb][s][0], pk[mb][s][1], pk[mb][s][2], pk[mb][s][3]};
;                 O = __builtin_amdgcn_mfma_f32_32x32x16_bf16(vf[k8], __builtin_bit_cast(bf16x8, pw), O, 0, 0, 0); }
;         }
; #pragma unroll
;         for (int rq = 0; rq < 4; ++rq) {
;             const unsigned w0 = cvt_pk_bf16(O[4 * rq] * inv, O[4 * rq + 1] * inv), w1 = cvt_pk_bf16(O[4 * rq + 2] * inv, O[4 * rq + 3] * inv);
;             *(u64*)(op + 32 * db + 8 * rq) = (u64)w0 | ((u64)w1 << 32);
;         }
;     }
;     ...
;     __syncthreads();
	v_mfma_f32_32x32x16_bf16 v[0:15], v[98:101], v[20:23], v[0:15]
	ds_read_b128 v[98:101], v176
	ds_read_b128 v[102:105], v178
	s_waitcnt lgkmcnt(1)
	v_mfma_f32_32x32x16_bf16 v[0:15], v[98:101], v[24:27], v[0:15]
	s_waitcnt lgkmcnt(0)
	v_mfma_f32_32x32x16_bf16 v[0:15], v[102:105], v[28:31], v[0:15]
	ds_read_b128 v[98:101], v177
	ds_read_b128 v[102:105], v180
	s_waitcnt lgkmcnt(1)
	v_mfma_f32_32x32x16_bf16 v[0:15], v[98:101], v[32:35], v[0:15]
	s_waitcnt lgkmcnt(0)
	v_mfma_f32_32x32x16_bf16 v[0:15], v[102:105], v[36:39], v[0:15]
	ds_read_b128 v[98:101], v179
	ds_read_b128 v[102:105], v181
	s_waitcnt lgkmcnt(1)
	v_mfma_f32_32x32x16_bf16 v[0:15], v[98:101], v[40:43], v[0:15]
	s_waitcnt lgkmcnt(0)
	v_mfma_f32_32x32x16_bf16 v[0:15], v[102:105], v[44:47], v[0:15]
	ds_read_b128 v[98:101], v182
	ds_read_b128 v[102:105], v184
	s_waitcnt lgkmcnt(1)
	v_mfma_f32_32x32x16_bf16 v[0:15], v[98:101], v[48:51], v[0:15]
	s_waitcnt lgkmcnt(0)
	v_mfma_f32_32x32x16_bf16 v[0:15], v[102:105], v[52:55], v[0:15]
	ds_read_b128 v[98:101], v185
	ds_read_b128 v[102:105], v187
	s_waitcnt lgkmcnt(1)
	v_mfma_f32_32x32x16_bf16 v[0:15], v[98:101], v[56:59], v[0:15]
	s_waitcnt lgkmcnt(0)
	v_mfma_f32_32x32x16_bf16 v[0:15], v[102:105], v[60:63], v[0:15]
	ds_read_b128 v[98:101], v186
	ds_read_b128 v[102:105], v189
	s_waitcnt lgkmcnt(1)
	v_mfma_f32_32x32x16_bf16 v[0:15], v[98:101], v[124:127], v[0:15]
	s_waitcnt lgkmcnt(0)
	v_mfma_f32_32x32x16_bf16 v[0:15], v[102:105], v[128:131], v[0:15]
	ds_read_b128 v[98:101], v188
	ds_read_b128 v[102:105], v190
	global_store_dwordx2 v[72:73], v[86:87], off offset:368
	s_waitcnt lgkmcnt(1)
	v_mfma_f32_32x32x16_bf16 v[0:15], v[98:101], v[64:67], v[0:15]
	s_waitcnt lgkmcnt(0)
	v_mfma_f32_32x32x16_bf16 v[0:15], v[102:105], v[68:71], v[0:15]
	s_nop 11
	v_mul_f32_e32 v0, v85, v0
	v_mul_f32_e32 v1, v85, v1
	v_mul_f32_e32 v2, v85, v2
	v_mul_f32_e32 v3, v85, v3
	v_cvt_pk_bf16_f32 v0, v0, v1
	v_cvt_pk_bf16_f32 v1, v2, v3
	v_mul_f32_e32 v4, v85, v4
	v_mul_f32_e32 v5, v85, v5
	v_mul_f32_e32 v6, v85, v6
	v_mul_f32_e32 v7, v85, v7
	global_store_dwordx2 v[72:73], v[0:1], off offset:384
	v_cvt_pk_bf16_f32 v0, v4, v5
	v_cvt_pk_bf16_f32 v1, v6, v7
	v_mul_f32_e32 v8, v85, v8
	v_mul_f32_e32 v9, v85, v9
	v_mul_f32_e32 v10, v85, v10
	v_mul_f32_e32 v11, v85, v11
	global_store_dwordx2 v[72:73], v[0:1], off offset:400
	v_cvt_pk_bf16_f32 v0, v8, v9
	v_cvt_pk_bf16_f32 v1, v10, v11
	v_mul_f32_e32 v12, v85, v12
	v_mul_f32_e32 v13, v85, v13
	v_mul_f32_e32 v14, v85, v14
	v_mul_f32_e32 v15, v85, v15
	global_store_dwordx2 v[72:73], v[0:1], off offset:416
	v_cvt_pk_bf16_f32 v86, v12, v13
	v_cvt_pk_bf16_f32 v87, v14, v15
	ds_read_b128 v[0:3], v191
	ds_read_b128 v[98:101], v192
	s_waitcnt lgkmcnt(1)
	v_mfma_f32_32x32x16_bf16 v[0:15], v[0:3], v[16:19], 0
	s_waitcnt lgkmcnt(0)
	v_mfma_f32_32x32x16_bf16 v[0:15], v[98:101], v[20:23], v[0:15]
	ds_read_b128 v[16:19], v96
	ds_read_b128 v[20:23], v92
	s_waitcnt lgkmcnt(1)
	v_mfma_f32_32x32x16_bf16 v[0:15], v[16:19], v[24:27], v[0:15]
	s_waitcnt lgkmcnt(0)
	v_mfma_f32_32x32x16_bf16 v[0:15], v[20:23], v[28:31], v[0:15]
	ds_read_b128 v[16:19], v88
	ds_read_b128 v[20:23], v80
	s_waitcnt lgkmcnt(1)
	v_mfma_f32_32x32x16_bf16 v[0:15], v[16:19], v[32:35], v[0:15]
	s_waitcnt lgkmcnt(0)
	v_mfma_f32_32x32x16_bf16 v[0:15], v[20:23], v[36:39], v[0:15]
	ds_read_b128 v[16:19], v76
	ds_read_b128 v[20:23], v74
	s_waitcnt lgkmcnt(1)
	v_mfma_f32_32x32x16_bf16 v[0:15], v[16:19], v[40:43], v[0:15]
	s_waitcnt lgkmcnt(0)
	v_mfma_f32_32x32x16_bf16 v[0:15], v[20:23], v[44:47], v[0:15]
	ds_read_b128 v[16:19], v75
	ds_read_b128 v[20:23], v77
	s_waitcnt lgkmcnt(1)
	v_mfma_f32_32x32x16_bf16 v[0:15], v[16:19], v[48:51], v[0:15]
	s_waitcnt lgkmcnt(0)
	v_mfma_f32_32x32x16_bf16 v[0:15], v[20:23], v[52:55], v[0:15]
	ds_read_b128 v[16:19], v78
	ds_read_b128 v[20:23], v81
	s_waitcnt lgkmcnt(1)
	v_mfma_f32_32x32x16_bf16 v[0:15], v[16:19], v[56:59], v[0:15]
	s_waitcnt lgkmcnt(0)
	v_mfma_f32_32x32x16_bf16 v[0:15], v[20:23], v[60:63], v[0:15]
	ds_read_b128 v[16:19], v79
	ds_read_b128 v[20:23], v83
	s_waitcnt lgkmcnt(1)
	v_mfma_f32_32x32x16_bf16 v[0:15], v[16:19], v[124:127], v[0:15]
	s_waitcnt lgkmcnt(0)
	v_mfma_f32_32x32x16_bf16 v[0:15], v[20:23], v[128:131], v[0:15]
	ds_read_b128 v[16:19], v82
	ds_read_b128 v[20:23], v84
	global_store_dwordx2 v[72:73], v[86:87], off offset:432
	s_waitcnt lgkmcnt(1)
	v_mfma_f32_32x32x16_bf16 v[0:15], v[16:19], v[64:67], v[0:15]
	s_waitcnt lgkmcnt(0)
	v_mfma_f32_32x32x16_bf16 v[0:15], v[20:23], v[68:71], v[0:15]
	s_nop 11
	v_mul_f32_e32 v0, v85, v0
	v_mul_f32_e32 v1, v85, v1
	v_mul_f32_e32 v2, v85, v2
	v_mul_f32_e32 v3, v85, v3
	v_cvt_pk_bf16_f32 v0, v0, v1
	v_cvt_pk_bf16_f32 v1, v2, v3
	v_mul_f32_e32 v4, v85, v4
	v_mul_f32_e32 v5, v85, v5
	v_mul_f32_e32 v6, v85, v6
	v_mul_f32_e32 v7, v85, v7
	global_store_dwordx2 v[72:73], v[0:1], off offset:448
	v_cvt_pk_bf16_f32 v0, v4, v5
	v_cvt_pk_bf16_f32 v1, v6, v7
	v_mul_f32_e32 v8, v85, v8
	v_mul_f32_e32 v9, v85, v9
	v_mul_f32_e32 v10, v85, v10
	v_mul_f32_e32 v11, v85, v11
	global_store_dwordx2 v[72:73], v[0:1], off offset:464
	v_cvt_pk_bf16_f32 v0, v8, v9
	v_cvt_pk_bf16_f32 v1, v10, v11
	v_mul_f32_e32 v12, v85, v12
	v_mul_f32_e32 v13, v85, v13
	v_mul_f32_e32 v14, v85, v14
	v_mul_f32_e32 v15, v85, v15
	global_store_dwordx2 v[72:73], v[0:1], off offset:480
	v_cvt_pk_bf16_f32 v0, v12, v13
	v_cvt_pk_bf16_f32 v1, v14, v15
	global_store_dwordx2 v[72:73], v[0:1], off offset:496
	s_barrier
